# GDN prep forward substitution blocked: rows 32..63 x columns 0..31 product on the f32 matrix cores (v_mfma_f32_32x32x2_f32, f32 operands and accumulate), halves the solve waves' VALU multiply-adds
# speedup vs baseline: 1.0056x; 1.0038x over previous
.LBB0_191:
	s_andn2_saveexec_b64 s[20:21], s[20:21]
	s_cbranch_execz .LBB0_43
	s_movk_i32 s0, 0x7f
	v_cmp_lt_u32_e32 vcc, s0, v49
	s_movk_i32 s0, 0x80
	v_lshlrev_b32_e32 v0, 1, v49
	v_cmp_gt_u32_e64 s[0:1], s0, v49
	v_and_b32_e32 v47, 0x7f, v49
	v_and_b32_e32 v0, 0xffffff00, v0
	v_cndmask_b32_e64 v2, v232, v223, s[0:1]
	v_add_u32_e32 v0, 0x1d700, v0
	v_lshl_or_b32 v2, v47, 1, v2
	v_mov_b32_e32 v3, 0x19100
	v_cndmask_b32_e64 v55, v228, v229, s[0:1]
	v_add_u32_e32 v53, 0, v0
	v_add_u32_e32 v51, 0, v2
	v_add_u32_e32 v57, 0, v3
	v_mov_b32_e32 v85, v1
	v_mov_b32_e32 v0, 0
	v_mov_b32_e32 v2, 0
	v_mov_b32_e32 v3, 0
	v_mov_b32_e32 v4, 0
	v_mov_b32_e32 v5, 0
	v_mov_b32_e32 v6, 0
	v_mov_b32_e32 v7, 0
	v_mov_b32_e32 v8, 0
	v_mov_b32_e32 v9, 0
	v_mov_b32_e32 v10, 0
	v_mov_b32_e32 v11, 0
	v_mov_b32_e32 v12, 0
	v_mov_b32_e32 v13, 0
	v_mov_b32_e32 v14, 0
	v_mov_b32_e32 v15, 0
	v_mov_b32_e32 v16, 0
	v_mov_b32_e32 v17, 0
	v_mov_b32_e32 v18, 0
	v_mov_b32_e32 v19, 0
	v_mov_b32_e32 v20, 0
	v_mov_b32_e32 v21, 0
	v_mov_b32_e32 v22, 0
	v_mov_b32_e32 v23, 0
	v_mov_b32_e32 v24, 0
	v_mov_b32_e32 v25, 0
	v_mov_b32_e32 v26, 0
	v_mov_b32_e32 v27, 0
	v_mov_b32_e32 v28, 0
	v_mov_b32_e32 v29, 0
	v_mov_b32_e32 v30, 0
	v_mov_b32_e32 v31, 0
	v_mov_b32_e32 v32, 0
	v_mov_b32_e32 v33, 0
	v_mov_b32_e32 v34, 0
	v_mov_b32_e32 v35, 0
	v_mov_b32_e32 v36, 0
	v_mov_b32_e32 v37, 0
	v_mov_b32_e32 v86, 0
	v_mov_b32_e32 v87, 0
	v_mov_b32_e32 v88, 0
	v_mov_b32_e32 v89, 0
	v_mov_b32_e32 v90, 0
	v_mov_b32_e32 v91, 0
	v_mov_b32_e32 v92, 0
	v_mov_b32_e32 v93, 0
	v_mov_b32_e32 v94, 0
	v_mov_b32_e32 v95, 0
	v_mov_b32_e32 v96, 0
	v_mov_b32_e32 v97, 0
	v_mov_b32_e32 v98, 0
	v_mov_b32_e32 v99, 0
	v_mov_b32_e32 v100, 0
	v_mov_b32_e32 v101, 0
	v_mov_b32_e32 v102, 0
	v_mov_b32_e32 v103, 0
	v_mov_b32_e32 v104, 0
	v_mov_b32_e32 v105, 0
	v_mov_b32_e32 v106, 0
	v_mov_b32_e32 v107, 0
	v_mov_b32_e32 v108, 0
	v_mov_b32_e32 v109, 0
	v_mov_b32_e32 v110, 0
	v_mov_b32_e32 v111, 0
	v_mov_b32_e32 v112, 0
	v_mov_b32_e32 v113, 0
	ds_read_u16 v221, v51
	ds_read_b32 v220, v53
	ds_read_b128 v[174:177], v57 offset:272
	v_mad_u32_u24 v61, v55, 1, v51
	ds_read_u16 v227, v61
	ds_read_b32 v226, v53 offset:4
	ds_read_b128 v[178:181], v57 offset:544
	v_mad_u32_u24 v61, v55, 2, v51
	ds_read_u16 v59, v61
	ds_read_b32 v204, v53 offset:8
	ds_read_b128 v[182:185], v57 offset:816
	s_waitcnt lgkmcnt(5)
	v_lshlrev_b32_e32 v221, 16, v221
	v_mul_f32_e32 v0, v220, v221
	v_mov_b32_e32 v2, v0
	v_mad_u32_u24 v61, v55, 3, v51
	ds_read_u16 v221, v61
	ds_read_b32 v220, v53 offset:12
	ds_read_b128 v[186:189], v57 offset:1088
	v_pk_fma_f32 v[250:251], v[174:175], v[2:3], 0 op_sel_hi:[1,1,0]
	v_pk_fma_f32 v[202:203], v[176:177], v[4:5], 0 op_sel_hi:[1,1,0]
	v_add_f32_e32 v250, v250, v251
	v_add_f32_e32 v202, v202, v203
	s_waitcnt lgkmcnt(5)
	v_lshlrev_b32_e32 v227, 16, v227
	v_add_f32_e32 v250, v250, v202
	v_fma_f32 v3, v226, v227, -v250
	v_mad_u32_u24 v61, v55, 4, v51
	ds_read_u16 v227, v61
	ds_read_b32 v226, v53 offset:16
	ds_read_b128 v[190:193], v57 offset:1360
	ds_read_b128 v[194:197], v57 offset:1376
	v_pk_fma_f32 v[246:247], v[178:179], v[2:3], 0 op_sel_hi:[1,1,0]
	v_pk_fma_f32 v[248:249], v[180:181], v[4:5], 0 op_sel_hi:[1,1,0]
	v_add_f32_e32 v246, v246, v247
	v_add_f32_e32 v248, v248, v249
	s_waitcnt lgkmcnt(5)
	v_lshlrev_b32_e32 v59, 16, v59
	v_add_f32_e32 v246, v246, v248
	v_fma_f32 v4, v204, v59, -v246
	v_mad_u32_u24 v61, v55, 5, v51
	ds_read_u16 v59, v61
	ds_read_b32 v204, v53 offset:20
	ds_read_b128 v[198:201], v57 offset:1632
	ds_read_b128 v[206:209], v57 offset:1648
	v_pk_fma_f32 v[250:251], v[182:183], v[2:3], 0 op_sel_hi:[1,1,0]
	v_pk_fma_f32 v[202:203], v[184:185], v[4:5], 0 op_sel_hi:[1,1,0]
	v_add_f32_e32 v250, v250, v251
	v_add_f32_e32 v202, v202, v203
	v_lshlrev_b32_e32 v221, 16, v221
	v_add_f32_e32 v250, v250, v202
	v_fma_f32 v5, v220, v221, -v250
	v_mad_u32_u24 v61, v55, 6, v51
	ds_read_u16 v221, v61
	ds_read_b32 v220, v53 offset:24
	ds_read_b128 v[210:213], v57 offset:1904
	ds_read_b128 v[214:217], v57 offset:1920
	s_waitcnt lgkmcnt(5)
	v_pk_fma_f32 v[246:247], v[186:187], v[2:3], 0 op_sel_hi:[1,1,0]
	v_pk_fma_f32 v[248:249], v[188:189], v[4:5], 0 op_sel_hi:[1,1,0]
	v_pk_fma_f32 v[250:251], v[190:191], v[2:3], 0 op_sel_hi:[1,1,0]
	v_pk_fma_f32 v[202:203], v[192:193], v[4:5], 0 op_sel_hi:[1,1,0]
	v_add_f32_e32 v246, v246, v247
	v_add_f32_e32 v248, v248, v249
	v_lshlrev_b32_e32 v227, 16, v227
	v_add_f32_e32 v246, v246, v248
	v_fma_f32 v6, v226, v227, -v246
	v_mad_u32_u24 v61, v55, 7, v51
	ds_read_u16 v227, v61
	ds_read_b32 v226, v53 offset:28
	ds_read_b128 v[238:241], v57 offset:2176
	ds_read_b128 v[242:245], v57 offset:2192
	v_pk_fma_f32 v[250:251], v[194:195], v[6:7], v[250:251]
	v_pk_fma_f32 v[202:203], v[196:197], v[8:9], v[202:203]
	v_pk_fma_f32 v[246:247], v[198:199], v[2:3], 0 op_sel_hi:[1,1,0]
	v_pk_fma_f32 v[248:249], v[200:201], v[4:5], 0 op_sel_hi:[1,1,0]
	v_add_f32_e32 v250, v250, v251
	v_add_f32_e32 v202, v202, v203
	v_lshlrev_b32_e32 v59, 16, v59
	v_add_f32_e32 v250, v250, v202
	v_fma_f32 v7, v204, v59, -v250
	v_mad_u32_u24 v61, v55, 8, v51
	ds_read_u16 v59, v61
	ds_read_b32 v204, v53 offset:32
	ds_read_b128 v[174:177], v57 offset:2448
	ds_read_b128 v[178:181], v57 offset:2464
	s_waitcnt lgkmcnt(5)
	v_pk_fma_f32 v[246:247], v[206:207], v[6:7], v[246:247]
	v_pk_fma_f32 v[248:249], v[208:209], v[8:9], v[248:249]
	ds_read_b128 v[182:185], v57 offset:2480
	v_pk_fma_f32 v[250:251], v[210:211], v[2:3], 0 op_sel_hi:[1,1,0]
	v_pk_fma_f32 v[202:203], v[212:213], v[4:5], 0 op_sel_hi:[1,1,0]
	v_add_f32_e32 v246, v246, v247
	v_add_f32_e32 v248, v248, v249
	v_lshlrev_b32_e32 v221, 16, v221
	v_add_f32_e32 v246, v246, v248
	v_fma_f32 v8, v220, v221, -v246
	v_mad_u32_u24 v61, v55, 9, v51
	ds_read_u16 v221, v61
	ds_read_b32 v220, v53 offset:36
	ds_read_b128 v[186:189], v57 offset:2720
	ds_read_b128 v[190:193], v57 offset:2736
	ds_read_b128 v[194:197], v57 offset:2752
	v_pk_fma_f32 v[250:251], v[214:215], v[6:7], v[250:251]
	v_pk_fma_f32 v[202:203], v[216:217], v[8:9], v[202:203]
	v_pk_fma_f32 v[246:247], v[238:239], v[2:3], 0 op_sel_hi:[1,1,0]
	v_pk_fma_f32 v[248:249], v[240:241], v[4:5], 0 op_sel_hi:[1,1,0]
	v_add_f32_e32 v250, v250, v251
	v_add_f32_e32 v202, v202, v203
	v_lshlrev_b32_e32 v227, 16, v227
	v_add_f32_e32 v250, v250, v202
	v_fma_f32 v9, v226, v227, -v250
	v_mad_u32_u24 v61, v55, 10, v51
	ds_read_u16 v227, v61
	ds_read_b32 v226, v53 offset:40
	s_waitcnt lgkmcnt(5)
	v_pk_fma_f32 v[246:247], v[242:243], v[6:7], v[246:247]
	v_pk_fma_f32 v[248:249], v[244:245], v[8:9], v[248:249]
	ds_read_b128 v[198:201], v57 offset:2992
	ds_read_b128 v[206:209], v57 offset:3008
	ds_read_b128 v[210:213], v57 offset:3024
	v_pk_fma_f32 v[250:251], v[174:175], v[2:3], 0 op_sel_hi:[1,1,0]
	v_pk_fma_f32 v[202:203], v[176:177], v[4:5], 0 op_sel_hi:[1,1,0]
	v_add_f32_e32 v246, v246, v247
	v_pk_fma_f32 v[250:251], v[178:179], v[6:7], v[250:251]
	v_pk_fma_f32 v[202:203], v[180:181], v[8:9], v[202:203]
	v_add_f32_e32 v248, v248, v249
	v_lshlrev_b32_e32 v59, 16, v59
	v_add_f32_e32 v246, v246, v248
	v_fma_f32 v10, v204, v59, -v246
	v_mad_u32_u24 v61, v55, 11, v51
	ds_read_u16 v59, v61
	ds_read_b32 v204, v53 offset:44
	ds_read_b128 v[214:217], v57 offset:3264
	ds_read_b128 v[238:241], v57 offset:3280
	ds_read_b128 v[242:245], v57 offset:3296
	v_pk_fma_f32 v[250:251], v[182:183], v[10:11], v[250:251]
	v_pk_fma_f32 v[202:203], v[184:185], v[12:13], v[202:203]
	s_waitcnt lgkmcnt(5)
	v_pk_fma_f32 v[246:247], v[186:187], v[2:3], 0 op_sel_hi:[1,1,0]
	v_pk_fma_f32 v[248:249], v[188:189], v[4:5], 0 op_sel_hi:[1,1,0]
	v_add_f32_e32 v250, v250, v251
	v_pk_fma_f32 v[246:247], v[190:191], v[6:7], v[246:247]
	v_pk_fma_f32 v[248:249], v[192:193], v[8:9], v[248:249]
	v_add_f32_e32 v202, v202, v203
	v_lshlrev_b32_e32 v221, 16, v221
	v_add_f32_e32 v250, v250, v202
	v_fma_f32 v11, v220, v221, -v250
	v_mad_u32_u24 v61, v55, 12, v51
	ds_read_u16 v221, v61
	ds_read_b32 v220, v53 offset:48
	ds_read_b128 v[174:177], v57 offset:3536
	ds_read_b128 v[178:181], v57 offset:3552
	ds_read_b128 v[182:185], v57 offset:3568
	ds_read_b128 v[186:189], v57 offset:3584
	v_pk_fma_f32 v[246:247], v[194:195], v[10:11], v[246:247]
	v_pk_fma_f32 v[248:249], v[196:197], v[12:13], v[248:249]
	v_pk_fma_f32 v[250:251], v[198:199], v[2:3], 0 op_sel_hi:[1,1,0]
	v_pk_fma_f32 v[202:203], v[200:201], v[4:5], 0 op_sel_hi:[1,1,0]
	v_add_f32_e32 v246, v246, v247
	v_pk_fma_f32 v[250:251], v[206:207], v[6:7], v[250:251]
	v_pk_fma_f32 v[202:203], v[208:209], v[8:9], v[202:203]
	v_add_f32_e32 v248, v248, v249
	v_lshlrev_b32_e32 v227, 16, v227
	v_add_f32_e32 v246, v246, v248
	v_fma_f32 v12, v226, v227, -v246
	v_mad_u32_u24 v61, v55, 13, v51
	ds_read_u16 v227, v61
	ds_read_b32 v226, v53 offset:52
	v_pk_fma_f32 v[250:251], v[210:211], v[10:11], v[250:251]
	v_pk_fma_f32 v[202:203], v[212:213], v[12:13], v[202:203]
	s_waitcnt lgkmcnt(5)
	v_pk_fma_f32 v[246:247], v[214:215], v[2:3], 0 op_sel_hi:[1,1,0]
	v_pk_fma_f32 v[248:249], v[216:217], v[4:5], 0 op_sel_hi:[1,1,0]
	ds_read_b128 v[190:193], v57 offset:3808
	ds_read_b128 v[194:197], v57 offset:3824
	ds_read_b128 v[198:201], v57 offset:3840
	ds_read_b128 v[206:209], v57 offset:3856
	v_add_f32_e32 v250, v250, v251
	v_pk_fma_f32 v[246:247], v[238:239], v[6:7], v[246:247]
	v_pk_fma_f32 v[248:249], v[240:241], v[8:9], v[248:249]
	v_add_f32_e32 v202, v202, v203
	v_lshlrev_b32_e32 v59, 16, v59
	v_add_f32_e32 v250, v250, v202
	v_fma_f32 v13, v204, v59, -v250
	v_mad_u32_u24 v61, v55, 14, v51
	ds_read_u16 v59, v61
	ds_read_b32 v204, v53 offset:56
	ds_read_b128 v[210:213], v57 offset:4080
	ds_read_b128 v[214:217], v57 offset:4096
	v_pk_fma_f32 v[246:247], v[242:243], v[10:11], v[246:247]
	v_pk_fma_f32 v[248:249], v[244:245], v[12:13], v[248:249]
	v_pk_fma_f32 v[250:251], v[174:175], v[2:3], 0 op_sel_hi:[1,1,0]
	v_pk_fma_f32 v[202:203], v[176:177], v[4:5], 0 op_sel_hi:[1,1,0]
	v_add_f32_e32 v246, v246, v247
	s_waitcnt lgkmcnt(5)
	v_pk_fma_f32 v[250:251], v[178:179], v[6:7], v[250:251]
	v_pk_fma_f32 v[202:203], v[180:181], v[8:9], v[202:203]
	ds_read_b128 v[238:241], v57 offset:4112
	ds_read_b128 v[242:245], v57 offset:4128
	v_add_f32_e32 v248, v248, v249
	v_pk_fma_f32 v[250:251], v[182:183], v[10:11], v[250:251]
	v_pk_fma_f32 v[202:203], v[184:185], v[12:13], v[202:203]
	v_lshlrev_b32_e32 v221, 16, v221
	v_add_f32_e32 v246, v246, v248
	v_fma_f32 v14, v220, v221, -v246
	v_mad_u32_u24 v61, v55, 15, v51
	ds_read_u16 v221, v61
	ds_read_b32 v220, v53 offset:60
	ds_read_b128 v[174:177], v57 offset:4352
	ds_read_b128 v[178:181], v57 offset:4368
	ds_read_b128 v[182:185], v57 offset:4384
	v_pk_fma_f32 v[250:251], v[186:187], v[14:15], v[250:251]
	v_pk_fma_f32 v[202:203], v[188:189], v[16:17], v[202:203]
	ds_read_b128 v[186:189], v57 offset:4400
	v_pk_fma_f32 v[246:247], v[190:191], v[2:3], 0 op_sel_hi:[1,1,0]
	v_pk_fma_f32 v[248:249], v[192:193], v[4:5], 0 op_sel_hi:[1,1,0]
	v_add_f32_e32 v250, v250, v251
	v_pk_fma_f32 v[246:247], v[194:195], v[6:7], v[246:247]
	v_pk_fma_f32 v[248:249], v[196:197], v[8:9], v[248:249]
	v_add_f32_e32 v202, v202, v203
	v_pk_fma_f32 v[246:247], v[198:199], v[10:11], v[246:247]
	v_pk_fma_f32 v[248:249], v[200:201], v[12:13], v[248:249]
	v_lshlrev_b32_e32 v227, 16, v227
	v_add_f32_e32 v250, v250, v202
	v_fma_f32 v15, v226, v227, -v250
	s_waitcnt lgkmcnt(5)
	v_pk_fma_f32 v[246:247], v[206:207], v[14:15], v[246:247]
	v_pk_fma_f32 v[248:249], v[208:209], v[16:17], v[248:249]
	v_mad_u32_u24 v61, v55, 16, v51
	ds_read_u16 v227, v61
	ds_read_b32 v226, v53 offset:64
	ds_read_b128 v[190:193], v57 offset:4624
	ds_read_b128 v[194:197], v57 offset:4640
	ds_read_b128 v[198:201], v57 offset:4656
	ds_read_b128 v[206:209], v57 offset:4672
	v_pk_fma_f32 v[250:251], v[210:211], v[2:3], 0 op_sel_hi:[1,1,0]
	v_pk_fma_f32 v[202:203], v[212:213], v[4:5], 0 op_sel_hi:[1,1,0]
	ds_read_b128 v[210:213], v57 offset:4688
	v_add_f32_e32 v246, v246, v247
	v_pk_fma_f32 v[250:251], v[214:215], v[6:7], v[250:251]
	v_pk_fma_f32 v[202:203], v[216:217], v[8:9], v[202:203]
	v_add_f32_e32 v248, v248, v249
	v_pk_fma_f32 v[250:251], v[238:239], v[10:11], v[250:251]
	v_pk_fma_f32 v[202:203], v[240:241], v[12:13], v[202:203]
	v_lshlrev_b32_e32 v59, 16, v59
	v_add_f32_e32 v246, v246, v248
	v_fma_f32 v16, v204, v59, -v246
	v_pk_fma_f32 v[250:251], v[242:243], v[14:15], v[250:251]
	v_pk_fma_f32 v[202:203], v[244:245], v[16:17], v[202:203]
	s_waitcnt lgkmcnt(5)
	v_pk_fma_f32 v[246:247], v[174:175], v[2:3], 0 op_sel_hi:[1,1,0]
	v_pk_fma_f32 v[248:249], v[176:177], v[4:5], 0 op_sel_hi:[1,1,0]
	v_mad_u32_u24 v61, v55, 17, v51
	ds_read_u16 v59, v61
	ds_read_b32 v204, v53 offset:68
	ds_read_b128 v[214:217], v57 offset:4896
	ds_read_b128 v[238:241], v57 offset:4912
	ds_read_b128 v[242:245], v57 offset:4928
	ds_read_b128 v[174:177], v57 offset:4944
	v_add_f32_e32 v250, v250, v251
	v_pk_fma_f32 v[246:247], v[178:179], v[6:7], v[246:247]
	v_pk_fma_f32 v[248:249], v[180:181], v[8:9], v[248:249]
	ds_read_b128 v[178:181], v57 offset:4960
	v_add_f32_e32 v202, v202, v203
	v_pk_fma_f32 v[246:247], v[182:183], v[10:11], v[246:247]
	v_pk_fma_f32 v[248:249], v[184:185], v[12:13], v[248:249]
	v_lshlrev_b32_e32 v221, 16, v221
	v_add_f32_e32 v250, v250, v202
	v_fma_f32 v17, v220, v221, -v250
	v_pk_fma_f32 v[246:247], v[186:187], v[14:15], v[246:247]
	v_pk_fma_f32 v[248:249], v[188:189], v[16:17], v[248:249]
	s_waitcnt lgkmcnt(5)
	v_pk_fma_f32 v[250:251], v[190:191], v[2:3], 0 op_sel_hi:[1,1,0]
	v_pk_fma_f32 v[202:203], v[192:193], v[4:5], 0 op_sel_hi:[1,1,0]
	v_mad_u32_u24 v61, v55, 18, v51
	ds_read_u16 v221, v61
	ds_read_b32 v220, v53 offset:72
	ds_read_b128 v[182:185], v57 offset:5168
	ds_read_b128 v[186:189], v57 offset:5184
	ds_read_b128 v[190:193], v57 offset:5200
	v_add_f32_e32 v246, v246, v247
	v_pk_fma_f32 v[250:251], v[194:195], v[6:7], v[250:251]
	v_pk_fma_f32 v[202:203], v[196:197], v[8:9], v[202:203]
	ds_read_b128 v[194:197], v57 offset:5216
	v_add_f32_e32 v248, v248, v249
	v_pk_fma_f32 v[250:251], v[198:199], v[10:11], v[250:251]
	v_pk_fma_f32 v[202:203], v[200:201], v[12:13], v[202:203]
	ds_read_b128 v[198:201], v57 offset:5232
	v_lshlrev_b32_e32 v227, 16, v227
	v_pk_fma_f32 v[250:251], v[206:207], v[14:15], v[250:251]
	v_pk_fma_f32 v[202:203], v[208:209], v[16:17], v[202:203]
	v_add_f32_e32 v246, v246, v248
	v_fma_f32 v18, v226, v227, -v246
	v_pk_fma_f32 v[250:251], v[210:211], v[18:19], v[250:251]
	v_pk_fma_f32 v[202:203], v[212:213], v[20:21], v[202:203]
	s_waitcnt lgkmcnt(5)
	v_pk_fma_f32 v[246:247], v[214:215], v[2:3], 0 op_sel_hi:[1,1,0]
	v_pk_fma_f32 v[248:249], v[216:217], v[4:5], 0 op_sel_hi:[1,1,0]
	v_mad_u32_u24 v61, v55, 19, v51
	ds_read_u16 v227, v61
	ds_read_b32 v226, v53 offset:76
	ds_read_b128 v[206:209], v57 offset:5440
	ds_read_b128 v[210:213], v57 offset:5456
	ds_read_b128 v[214:217], v57 offset:5472
	v_add_f32_e32 v250, v250, v251
	v_pk_fma_f32 v[246:247], v[238:239], v[6:7], v[246:247]
	v_pk_fma_f32 v[248:249], v[240:241], v[8:9], v[248:249]
	ds_read_b128 v[238:241], v57 offset:5488
	v_add_f32_e32 v202, v202, v203
	v_pk_fma_f32 v[246:247], v[242:243], v[10:11], v[246:247]
	v_pk_fma_f32 v[248:249], v[244:245], v[12:13], v[248:249]
	ds_read_b128 v[242:245], v57 offset:5504
	v_lshlrev_b32_e32 v59, 16, v59
	v_pk_fma_f32 v[246:247], v[174:175], v[14:15], v[246:247]
	v_pk_fma_f32 v[248:249], v[176:177], v[16:17], v[248:249]
	v_add_f32_e32 v250, v250, v202
	v_fma_f32 v19, v204, v59, -v250
	v_pk_fma_f32 v[246:247], v[178:179], v[18:19], v[246:247]
	v_pk_fma_f32 v[248:249], v[180:181], v[20:21], v[248:249]
	s_waitcnt lgkmcnt(5)
	v_pk_fma_f32 v[250:251], v[182:183], v[2:3], 0 op_sel_hi:[1,1,0]
	v_pk_fma_f32 v[202:203], v[184:185], v[4:5], 0 op_sel_hi:[1,1,0]
	v_mad_u32_u24 v61, v55, 20, v51
	ds_read_u16 v59, v61
	ds_read_b32 v204, v53 offset:80
	ds_read_b128 v[174:177], v57 offset:5712
	ds_read_b128 v[178:181], v57 offset:5728
	ds_read_b128 v[182:185], v57 offset:5744
	v_add_f32_e32 v246, v246, v247
	v_pk_fma_f32 v[250:251], v[186:187], v[6:7], v[250:251]
	v_pk_fma_f32 v[202:203], v[188:189], v[8:9], v[202:203]
	ds_read_b128 v[186:189], v57 offset:5760
	v_add_f32_e32 v248, v248, v249
	v_pk_fma_f32 v[250:251], v[190:191], v[10:11], v[250:251]
	v_pk_fma_f32 v[202:203], v[192:193], v[12:13], v[202:203]
	ds_read_b128 v[190:193], v57 offset:5776
	v_lshlrev_b32_e32 v221, 16, v221
	v_pk_fma_f32 v[250:251], v[194:195], v[14:15], v[250:251]
	v_pk_fma_f32 v[202:203], v[196:197], v[16:17], v[202:203]
	ds_read_b128 v[194:197], v57 offset:5792
	v_add_f32_e32 v246, v246, v248
	v_fma_f32 v20, v220, v221, -v246
	v_pk_fma_f32 v[250:251], v[198:199], v[18:19], v[250:251]
	v_pk_fma_f32 v[202:203], v[200:201], v[20:21], v[202:203]
	s_waitcnt lgkmcnt(5)
	v_pk_fma_f32 v[246:247], v[206:207], v[2:3], 0 op_sel_hi:[1,1,0]
	v_pk_fma_f32 v[248:249], v[208:209], v[4:5], 0 op_sel_hi:[1,1,0]
	v_mad_u32_u24 v61, v55, 21, v51
	ds_read_u16 v221, v61
	ds_read_b32 v220, v53 offset:84
	ds_read_b128 v[198:201], v57 offset:5984
	ds_read_b128 v[206:209], v57 offset:6000
	v_add_f32_e32 v250, v250, v251
	v_pk_fma_f32 v[246:247], v[210:211], v[6:7], v[246:247]
	v_pk_fma_f32 v[248:249], v[212:213], v[8:9], v[248:249]
	ds_read_b128 v[210:213], v57 offset:6016
	v_add_f32_e32 v202, v202, v203
	v_pk_fma_f32 v[246:247], v[214:215], v[10:11], v[246:247]
	v_pk_fma_f32 v[248:249], v[216:217], v[12:13], v[248:249]
	ds_read_b128 v[214:217], v57 offset:6032
	v_lshlrev_b32_e32 v227, 16, v227
	v_pk_fma_f32 v[246:247], v[238:239], v[14:15], v[246:247]
	v_pk_fma_f32 v[248:249], v[240:241], v[16:17], v[248:249]
	ds_read_b128 v[238:241], v57 offset:6048
	v_add_f32_e32 v250, v250, v202
	v_fma_f32 v21, v226, v227, -v250
	v_pk_fma_f32 v[246:247], v[242:243], v[18:19], v[246:247]
	v_pk_fma_f32 v[248:249], v[244:245], v[20:21], v[248:249]
	ds_read_b128 v[242:245], v57 offset:6064
	v_pk_fma_f32 v[250:251], v[174:175], v[2:3], 0 op_sel_hi:[1,1,0]
	v_pk_fma_f32 v[202:203], v[176:177], v[4:5], 0 op_sel_hi:[1,1,0]
	v_add_f32_e32 v246, v246, v247
	s_waitcnt lgkmcnt(5)
	v_pk_fma_f32 v[250:251], v[178:179], v[6:7], v[250:251]
	v_pk_fma_f32 v[202:203], v[180:181], v[8:9], v[202:203]
	v_mad_u32_u24 v61, v55, 22, v51
	ds_read_u16 v227, v61
	ds_read_b32 v226, v53 offset:88
	ds_read_b128 v[174:177], v57 offset:6256
	ds_read_b128 v[178:181], v57 offset:6272
	v_add_f32_e32 v248, v248, v249
	v_pk_fma_f32 v[250:251], v[182:183], v[10:11], v[250:251]
	v_pk_fma_f32 v[202:203], v[184:185], v[12:13], v[202:203]
	ds_read_b128 v[182:185], v57 offset:6288
	v_lshlrev_b32_e32 v59, 16, v59
	v_pk_fma_f32 v[250:251], v[186:187], v[14:15], v[250:251]
	v_pk_fma_f32 v[202:203], v[188:189], v[16:17], v[202:203]
	ds_read_b128 v[186:189], v57 offset:6304
	v_add_f32_e32 v246, v246, v248
	v_pk_fma_f32 v[250:251], v[190:191], v[18:19], v[250:251]
	v_pk_fma_f32 v[202:203], v[192:193], v[20:21], v[202:203]
	ds_read_b128 v[190:193], v57 offset:6320
	v_fma_f32 v22, v204, v59, -v246
	v_pk_fma_f32 v[250:251], v[194:195], v[22:23], v[250:251]
	v_pk_fma_f32 v[202:203], v[196:197], v[24:25], v[202:203]
	ds_read_b128 v[194:197], v57 offset:6336
	v_pk_fma_f32 v[246:247], v[198:199], v[2:3], 0 op_sel_hi:[1,1,0]
	v_pk_fma_f32 v[248:249], v[200:201], v[4:5], 0 op_sel_hi:[1,1,0]
	v_add_f32_e32 v250, v250, v251
	s_waitcnt lgkmcnt(5)
	v_pk_fma_f32 v[246:247], v[206:207], v[6:7], v[246:247]
	v_pk_fma_f32 v[248:249], v[208:209], v[8:9], v[248:249]
	v_mad_u32_u24 v61, v55, 23, v51
	ds_read_u16 v59, v61
	ds_read_b32 v204, v53 offset:92
	ds_read_b128 v[198:201], v57 offset:6528
	ds_read_b128 v[206:209], v57 offset:6544
	v_add_f32_e32 v202, v202, v203
	v_pk_fma_f32 v[246:247], v[210:211], v[10:11], v[246:247]
	v_pk_fma_f32 v[248:249], v[212:213], v[12:13], v[248:249]
	ds_read_b128 v[210:213], v57 offset:6560
	v_lshlrev_b32_e32 v221, 16, v221
	v_pk_fma_f32 v[246:247], v[214:215], v[14:15], v[246:247]
	v_pk_fma_f32 v[248:249], v[216:217], v[16:17], v[248:249]
	ds_read_b128 v[214:217], v57 offset:6576
	v_add_f32_e32 v250, v250, v202
	v_pk_fma_f32 v[246:247], v[238:239], v[18:19], v[246:247]
	v_pk_fma_f32 v[248:249], v[240:241], v[20:21], v[248:249]
	ds_read_b128 v[238:241], v57 offset:6592
	v_fma_f32 v23, v220, v221, -v250
	v_pk_fma_f32 v[246:247], v[242:243], v[22:23], v[246:247]
	v_pk_fma_f32 v[248:249], v[244:245], v[24:25], v[248:249]
	ds_read_b128 v[242:245], v57 offset:6608
	v_pk_fma_f32 v[250:251], v[174:175], v[2:3], 0 op_sel_hi:[1,1,0]
	v_pk_fma_f32 v[202:203], v[176:177], v[4:5], 0 op_sel_hi:[1,1,0]
	v_add_f32_e32 v246, v246, v247
	s_waitcnt lgkmcnt(5)
	v_pk_fma_f32 v[250:251], v[178:179], v[6:7], v[250:251]
	v_pk_fma_f32 v[202:203], v[180:181], v[8:9], v[202:203]
	v_mad_u32_u24 v61, v55, 24, v51
	ds_read_u16 v221, v61
	ds_read_b32 v220, v53 offset:96
	ds_read_b128 v[174:177], v57 offset:6800
	ds_read_b128 v[178:181], v57 offset:6816
	v_add_f32_e32 v248, v248, v249
	v_pk_fma_f32 v[250:251], v[182:183], v[10:11], v[250:251]
	v_pk_fma_f32 v[202:203], v[184:185], v[12:13], v[202:203]
	ds_read_b128 v[182:185], v57 offset:6832
	v_lshlrev_b32_e32 v227, 16, v227
	v_pk_fma_f32 v[250:251], v[186:187], v[14:15], v[250:251]
	v_pk_fma_f32 v[202:203], v[188:189], v[16:17], v[202:203]
	ds_read_b128 v[186:189], v57 offset:6848
	v_add_f32_e32 v246, v246, v248
	v_pk_fma_f32 v[250:251], v[190:191], v[18:19], v[250:251]
	v_pk_fma_f32 v[202:203], v[192:193], v[20:21], v[202:203]
	ds_read_b128 v[190:193], v57 offset:6864
	v_fma_f32 v24, v226, v227, -v246
	v_pk_fma_f32 v[250:251], v[194:195], v[22:23], v[250:251]
	v_pk_fma_f32 v[202:203], v[196:197], v[24:25], v[202:203]
	ds_read_b128 v[194:197], v57 offset:6880
	v_pk_fma_f32 v[246:247], v[198:199], v[2:3], 0 op_sel_hi:[1,1,0]
	v_pk_fma_f32 v[248:249], v[200:201], v[4:5], 0 op_sel_hi:[1,1,0]
	v_add_f32_e32 v250, v250, v251
	s_waitcnt lgkmcnt(5)
	v_pk_fma_f32 v[246:247], v[206:207], v[6:7], v[246:247]
	v_pk_fma_f32 v[248:249], v[208:209], v[8:9], v[248:249]
	ds_read_b128 v[198:201], v57 offset:6896
	v_mad_u32_u24 v61, v55, 25, v51
	ds_read_u16 v227, v61
	ds_read_b32 v226, v53 offset:100
	ds_read_b128 v[206:209], v57 offset:7072
	v_add_f32_e32 v202, v202, v203
	v_pk_fma_f32 v[246:247], v[210:211], v[10:11], v[246:247]
	v_pk_fma_f32 v[248:249], v[212:213], v[12:13], v[248:249]
	ds_read_b128 v[210:213], v57 offset:7088
	v_lshlrev_b32_e32 v59, 16, v59
	v_pk_fma_f32 v[246:247], v[214:215], v[14:15], v[246:247]
	v_pk_fma_f32 v[248:249], v[216:217], v[16:17], v[248:249]
	ds_read_b128 v[214:217], v57 offset:7104
	v_add_f32_e32 v250, v250, v202
	v_pk_fma_f32 v[246:247], v[238:239], v[18:19], v[246:247]
	v_pk_fma_f32 v[248:249], v[240:241], v[20:21], v[248:249]
	ds_read_b128 v[238:241], v57 offset:7120
	v_fma_f32 v25, v204, v59, -v250
	v_pk_fma_f32 v[246:247], v[242:243], v[22:23], v[246:247]
	v_pk_fma_f32 v[248:249], v[244:245], v[24:25], v[248:249]
	ds_read_b128 v[242:245], v57 offset:7136
	v_pk_fma_f32 v[250:251], v[174:175], v[2:3], 0 op_sel_hi:[1,1,0]
	v_pk_fma_f32 v[202:203], v[176:177], v[4:5], 0 op_sel_hi:[1,1,0]
	v_add_f32_e32 v246, v246, v247
	s_waitcnt lgkmcnt(5)
	v_pk_fma_f32 v[250:251], v[178:179], v[6:7], v[250:251]
	v_pk_fma_f32 v[202:203], v[180:181], v[8:9], v[202:203]
	ds_read_b128 v[174:177], v57 offset:7152
	ds_read_b128 v[178:181], v57 offset:7168
	v_mad_u32_u24 v61, v55, 26, v51
	ds_read_u16 v59, v61
	ds_read_b32 v204, v53 offset:104
	v_add_f32_e32 v248, v248, v249
	v_pk_fma_f32 v[250:251], v[182:183], v[10:11], v[250:251]
	v_pk_fma_f32 v[202:203], v[184:185], v[12:13], v[202:203]
	ds_read_b128 v[182:185], v57 offset:7344
	v_lshlrev_b32_e32 v221, 16, v221
	v_pk_fma_f32 v[250:251], v[186:187], v[14:15], v[250:251]
	v_pk_fma_f32 v[202:203], v[188:189], v[16:17], v[202:203]
	ds_read_b128 v[186:189], v57 offset:7360
	v_add_f32_e32 v246, v246, v248
	v_pk_fma_f32 v[250:251], v[190:191], v[18:19], v[250:251]
	v_pk_fma_f32 v[202:203], v[192:193], v[20:21], v[202:203]
	ds_read_b128 v[190:193], v57 offset:7376
	v_fma_f32 v26, v220, v221, -v246
	v_pk_fma_f32 v[250:251], v[194:195], v[22:23], v[250:251]
	v_pk_fma_f32 v[202:203], v[196:197], v[24:25], v[202:203]
	ds_read_b128 v[194:197], v57 offset:7392
	v_pk_fma_f32 v[250:251], v[198:199], v[26:27], v[250:251]
	v_pk_fma_f32 v[202:203], v[200:201], v[28:29], v[202:203]
	s_waitcnt lgkmcnt(5)
	v_pk_fma_f32 v[246:247], v[206:207], v[2:3], 0 op_sel_hi:[1,1,0]
	v_pk_fma_f32 v[248:249], v[208:209], v[4:5], 0 op_sel_hi:[1,1,0]
	ds_read_b128 v[198:201], v57 offset:7408
	ds_read_b128 v[206:209], v57 offset:7424
	v_add_f32_e32 v250, v250, v251
	v_pk_fma_f32 v[246:247], v[210:211], v[6:7], v[246:247]
	v_pk_fma_f32 v[248:249], v[212:213], v[8:9], v[248:249]
	ds_read_b128 v[210:213], v57 offset:7440
	v_mad_u32_u24 v61, v55, 27, v51
	ds_read_u16 v221, v61
	ds_read_b32 v220, v53 offset:108
	v_add_f32_e32 v202, v202, v203
	v_pk_fma_f32 v[246:247], v[214:215], v[10:11], v[246:247]
	v_pk_fma_f32 v[248:249], v[216:217], v[12:13], v[248:249]
	ds_read_b128 v[214:217], v57 offset:7616
	v_lshlrev_b32_e32 v227, 16, v227
	v_pk_fma_f32 v[246:247], v[238:239], v[14:15], v[246:247]
	v_pk_fma_f32 v[248:249], v[240:241], v[16:17], v[248:249]
	ds_read_b128 v[238:241], v57 offset:7632
	v_add_f32_e32 v250, v250, v202
	v_pk_fma_f32 v[246:247], v[242:243], v[18:19], v[246:247]
	v_pk_fma_f32 v[248:249], v[244:245], v[20:21], v[248:249]
	ds_read_b128 v[242:245], v57 offset:7648
	v_fma_f32 v27, v226, v227, -v250
	v_pk_fma_f32 v[246:247], v[174:175], v[22:23], v[246:247]
	v_pk_fma_f32 v[248:249], v[176:177], v[24:25], v[248:249]
	v_pk_fma_f32 v[246:247], v[178:179], v[26:27], v[246:247]
	v_pk_fma_f32 v[248:249], v[180:181], v[28:29], v[248:249]
	s_waitcnt lgkmcnt(5)
	v_pk_fma_f32 v[250:251], v[182:183], v[2:3], 0 op_sel_hi:[1,1,0]
	v_pk_fma_f32 v[202:203], v[184:185], v[4:5], 0 op_sel_hi:[1,1,0]
	ds_read_b128 v[174:177], v57 offset:7664
	ds_read_b128 v[178:181], v57 offset:7680
	ds_read_b128 v[182:185], v57 offset:7696
	v_add_f32_e32 v246, v246, v247
	v_pk_fma_f32 v[250:251], v[186:187], v[6:7], v[250:251]
	v_pk_fma_f32 v[202:203], v[188:189], v[8:9], v[202:203]
	ds_read_b128 v[186:189], v57 offset:7712
	v_mad_u32_u24 v61, v55, 28, v51
	ds_read_u16 v227, v61
	ds_read_b32 v226, v53 offset:112
	v_add_f32_e32 v248, v248, v249
	v_pk_fma_f32 v[250:251], v[190:191], v[10:11], v[250:251]
	v_pk_fma_f32 v[202:203], v[192:193], v[12:13], v[202:203]
	ds_read_b128 v[190:193], v57 offset:7888
	v_lshlrev_b32_e32 v59, 16, v59
	v_pk_fma_f32 v[250:251], v[194:195], v[14:15], v[250:251]
	v_pk_fma_f32 v[202:203], v[196:197], v[16:17], v[202:203]
	ds_read_b128 v[194:197], v57 offset:7904
	v_add_f32_e32 v246, v246, v248
	v_pk_fma_f32 v[250:251], v[198:199], v[18:19], v[250:251]
	v_pk_fma_f32 v[202:203], v[200:201], v[20:21], v[202:203]
	v_fma_f32 v28, v204, v59, -v246
	v_pk_fma_f32 v[250:251], v[206:207], v[22:23], v[250:251]
	v_pk_fma_f32 v[202:203], v[208:209], v[24:25], v[202:203]
	v_pk_fma_f32 v[250:251], v[210:211], v[26:27], v[250:251]
	v_pk_fma_f32 v[202:203], v[212:213], v[28:29], v[202:203]
	s_waitcnt lgkmcnt(5)
	v_pk_fma_f32 v[246:247], v[214:215], v[2:3], 0 op_sel_hi:[1,1,0]
	v_pk_fma_f32 v[248:249], v[216:217], v[4:5], 0 op_sel_hi:[1,1,0]
	ds_read_b128 v[198:201], v57 offset:7920
	ds_read_b128 v[206:209], v57 offset:7936
	ds_read_b128 v[210:213], v57 offset:7952
	ds_read_b128 v[214:217], v57 offset:7968
	v_add_f32_e32 v250, v250, v251
	v_pk_fma_f32 v[246:247], v[238:239], v[6:7], v[246:247]
	v_pk_fma_f32 v[248:249], v[240:241], v[8:9], v[248:249]
	ds_read_b128 v[238:241], v57 offset:7984
	v_add_f32_e32 v202, v202, v203
	v_pk_fma_f32 v[246:247], v[242:243], v[10:11], v[246:247]
	v_pk_fma_f32 v[248:249], v[244:245], v[12:13], v[248:249]
	ds_read_b128 v[242:245], v57 offset:8000
	v_mad_u32_u24 v61, v55, 29, v51
	ds_read_u16 v59, v61
	ds_read_b32 v204, v53 offset:116
	v_lshlrev_b32_e32 v221, 16, v221
	v_pk_fma_f32 v[246:247], v[174:175], v[14:15], v[246:247]
	v_pk_fma_f32 v[248:249], v[176:177], v[16:17], v[248:249]
	v_add_f32_e32 v250, v250, v202
	v_pk_fma_f32 v[246:247], v[178:179], v[18:19], v[246:247]
	v_pk_fma_f32 v[248:249], v[180:181], v[20:21], v[248:249]
	v_fma_f32 v29, v220, v221, -v250
	v_pk_fma_f32 v[246:247], v[182:183], v[22:23], v[246:247]
	v_pk_fma_f32 v[248:249], v[184:185], v[24:25], v[248:249]
	s_waitcnt lgkmcnt(5)
	v_pk_fma_f32 v[246:247], v[186:187], v[26:27], v[246:247]
	v_pk_fma_f32 v[248:249], v[188:189], v[28:29], v[248:249]
	ds_read_b128 v[174:177], v57 offset:8160
	ds_read_b128 v[178:181], v57 offset:8176
	ds_read_b128 v[182:185], v57 offset:8192
	ds_read_b128 v[186:189], v57 offset:8208
	v_pk_fma_f32 v[250:251], v[190:191], v[2:3], 0 op_sel_hi:[1,1,0]
	v_pk_fma_f32 v[202:203], v[192:193], v[4:5], 0 op_sel_hi:[1,1,0]
	ds_read_b128 v[190:193], v57 offset:8224
	v_add_f32_e32 v246, v246, v247
	v_pk_fma_f32 v[250:251], v[194:195], v[6:7], v[250:251]
	v_pk_fma_f32 v[202:203], v[196:197], v[8:9], v[202:203]
	ds_read_b128 v[194:197], v57 offset:8240
	v_add_f32_e32 v248, v248, v249
	v_pk_fma_f32 v[250:251], v[198:199], v[10:11], v[250:251]
	v_pk_fma_f32 v[202:203], v[200:201], v[12:13], v[202:203]
	ds_read_b128 v[198:201], v57 offset:8256
	v_lshlrev_b32_e32 v227, 16, v227
	v_pk_fma_f32 v[250:251], v[206:207], v[14:15], v[250:251]
	v_pk_fma_f32 v[202:203], v[208:209], v[16:17], v[202:203]
	ds_read_b128 v[206:209], v57 offset:8272
	v_add_f32_e32 v246, v246, v248
	v_pk_fma_f32 v[250:251], v[210:211], v[18:19], v[250:251]
	v_pk_fma_f32 v[202:203], v[212:213], v[20:21], v[202:203]
	v_fma_f32 v30, v226, v227, -v246
	s_waitcnt lgkmcnt(5)
	v_pk_fma_f32 v[250:251], v[214:215], v[22:23], v[250:251]
	v_pk_fma_f32 v[202:203], v[216:217], v[24:25], v[202:203]
	v_mad_u32_u24 v61, v55, 30, v51
	ds_read_u16 v221, v61
	ds_read_b32 v220, v53 offset:120
	ds_read_b128 v[210:213], v57 offset:8432
	ds_read_b128 v[214:217], v57 offset:8448
	v_pk_fma_f32 v[250:251], v[238:239], v[26:27], v[250:251]
	v_pk_fma_f32 v[202:203], v[240:241], v[28:29], v[202:203]
	ds_read_b128 v[238:241], v57 offset:8464
	v_pk_fma_f32 v[250:251], v[242:243], v[30:31], v[250:251]
	v_pk_fma_f32 v[202:203], v[244:245], v[32:33], v[202:203]
	ds_read_b128 v[242:245], v57 offset:8480
	v_pk_fma_f32 v[246:247], v[174:175], v[2:3], 0 op_sel_hi:[1,1,0]
	v_pk_fma_f32 v[248:249], v[176:177], v[4:5], 0 op_sel_hi:[1,1,0]
	ds_read_b128 v[174:177], v57 offset:8496
	v_add_f32_e32 v250, v250, v251
	v_pk_fma_f32 v[246:247], v[178:179], v[6:7], v[246:247]
	v_pk_fma_f32 v[248:249], v[180:181], v[8:9], v[248:249]
	ds_read_b128 v[178:181], v57 offset:8512
	v_add_f32_e32 v202, v202, v203
	v_pk_fma_f32 v[246:247], v[182:183], v[10:11], v[246:247]
	v_pk_fma_f32 v[248:249], v[184:185], v[12:13], v[248:249]
	v_lshlrev_b32_e32 v59, 16, v59
	s_waitcnt lgkmcnt(5)
	v_pk_fma_f32 v[246:247], v[186:187], v[14:15], v[246:247]
	v_pk_fma_f32 v[248:249], v[188:189], v[16:17], v[248:249]
	ds_read_b128 v[182:185], v57 offset:8528
	ds_read_b128 v[186:189], v57 offset:8544
	v_mad_u32_u24 v61, v55, 31, v51
	ds_read_u16 v227, v61
	ds_read_b32 v226, v53 offset:124
	v_add_f32_e32 v250, v250, v202
	v_pk_fma_f32 v[246:247], v[190:191], v[18:19], v[246:247]
	v_pk_fma_f32 v[248:249], v[192:193], v[20:21], v[248:249]
	v_fma_f32 v31, v204, v59, -v250
	v_mad_u32_u24 v61, v55, 32, v51
	ds_read_u16 v59, v61
	ds_read_b32 v204, v53 offset:128
	v_pk_fma_f32 v[246:247], v[194:195], v[22:23], v[246:247]
	v_pk_fma_f32 v[248:249], v[196:197], v[24:25], v[248:249]
	v_pk_fma_f32 v[246:247], v[198:199], v[26:27], v[246:247]
	v_pk_fma_f32 v[248:249], v[200:201], v[28:29], v[248:249]
	ds_read_b128 v[198:201], v57 offset:9104
	v_pk_fma_f32 v[246:247], v[206:207], v[30:31], v[246:247]
	v_pk_fma_f32 v[248:249], v[208:209], v[32:33], v[248:249]
	v_pk_fma_f32 v[250:251], v[210:211], v[2:3], 0 op_sel_hi:[1,1,0]
	v_pk_fma_f32 v[202:203], v[212:213], v[4:5], 0 op_sel_hi:[1,1,0]
	v_add_f32_e32 v246, v246, v247
	s_waitcnt lgkmcnt(5)
	v_pk_fma_f32 v[250:251], v[214:215], v[6:7], v[250:251]
	v_pk_fma_f32 v[202:203], v[216:217], v[8:9], v[202:203]
	v_add_f32_e32 v248, v248, v249
	v_pk_fma_f32 v[250:251], v[238:239], v[10:11], v[250:251]
	v_pk_fma_f32 v[202:203], v[240:241], v[12:13], v[202:203]
	v_lshlrev_b32_e32 v221, 16, v221
	v_pk_fma_f32 v[250:251], v[242:243], v[14:15], v[250:251]
	v_pk_fma_f32 v[202:203], v[244:245], v[16:17], v[202:203]
	v_add_f32_e32 v246, v246, v248
	v_pk_fma_f32 v[250:251], v[174:175], v[18:19], v[250:251]
	v_pk_fma_f32 v[202:203], v[176:177], v[20:21], v[202:203]
	v_fma_f32 v32, v220, v221, -v246
	v_mad_u32_u24 v61, v55, 33, v51
	ds_read_u16 v221, v61
	ds_read_b32 v220, v53 offset:132
	ds_read_b128 v[206:209], v57 offset:9376
	v_pk_fma_f32 v[250:251], v[178:179], v[22:23], v[250:251]
	v_pk_fma_f32 v[202:203], v[180:181], v[24:25], v[202:203]
	v_pk_fma_f32 v[250:251], v[182:183], v[26:27], v[250:251]
	v_pk_fma_f32 v[202:203], v[184:185], v[28:29], v[202:203]
	v_pk_fma_f32 v[250:251], v[186:187], v[30:31], v[250:251]
	v_pk_fma_f32 v[202:203], v[188:189], v[32:33], v[202:203]
	v_add_f32_e32 v250, v250, v251
	v_add_f32_e32 v202, v202, v203
	s_waitcnt lgkmcnt(5)
	v_lshlrev_b32_e32 v227, 16, v227
	v_add_f32_e32 v250, v250, v202
	v_fma_f32 v33, v226, v227, -v250
	v_mad_u32_u24 v61, v55, 34, v51
	ds_read_u16 v227, v61
	ds_read_b32 v226, v53 offset:136
	ds_read_b128 v[210:213], v57 offset:9648
	s_waitcnt lgkmcnt(6)
	v_and_b32_e32 v203, 31, v222
	v_mul_u32_u24_e32 v203, 0x110, v203
	v_lshrrev_b32_e32 v202, 5, v222
	v_lshl_add_u32 v202, v202, 2, v203
	v_add_u32_e32 v202, v202, v57
	ds_read_b32 v190, v202 offset:8704
	ds_read_b32 v191, v202 offset:8712
	ds_read_b32 v192, v202 offset:8720
	ds_read_b32 v193, v202 offset:8728
	ds_read_b32 v194, v202 offset:8736
	ds_read_b32 v195, v202 offset:8744
	ds_read_b32 v196, v202 offset:8752
	ds_read_b32 v197, v202 offset:8760
	v_mov_b32_e32 v246, v0
	v_mov_b32_e32 v247, v3
	s_nop 1
	v_permlane32_swap_b32_e32 v246, v247
	s_waitcnt lgkmcnt(7)
	s_nop 1
	v_mfma_f32_32x32x2_f32 v[174:189], v190, v246, 0
	v_mfma_f32_32x32x2_f32 v[98:113], v190, v247, 0
	ds_read_b32 v190, v202 offset:8768
	v_mov_b32_e32 v248, v4
	v_mov_b32_e32 v249, v5
	s_nop 1
	v_permlane32_swap_b32_e32 v248, v249
	s_waitcnt lgkmcnt(7)
	s_nop 1
	v_mfma_f32_32x32x2_f32 v[174:189], v191, v248, v[174:189]
	v_mfma_f32_32x32x2_f32 v[98:113], v191, v249, v[98:113]
	ds_read_b32 v191, v202 offset:8776
	v_mov_b32_e32 v250, v6
	v_mov_b32_e32 v251, v7
	s_nop 1
	v_permlane32_swap_b32_e32 v250, v251
	s_waitcnt lgkmcnt(7)
	s_nop 1
	v_mfma_f32_32x32x2_f32 v[174:189], v192, v250, v[174:189]
	v_mfma_f32_32x32x2_f32 v[98:113], v192, v251, v[98:113]
	ds_read_b32 v192, v202 offset:8784
	v_mov_b32_e32 v246, v8
	v_mov_b32_e32 v247, v9
	s_nop 1
	v_permlane32_swap_b32_e32 v246, v247
	s_waitcnt lgkmcnt(7)
	s_nop 1
	v_mfma_f32_32x32x2_f32 v[174:189], v193, v246, v[174:189]
	v_mfma_f32_32x32x2_f32 v[98:113], v193, v247, v[98:113]
	ds_read_b32 v193, v202 offset:8792
	v_mov_b32_e32 v248, v10
	v_mov_b32_e32 v249, v11
	s_nop 1
	v_permlane32_swap_b32_e32 v248, v249
	s_waitcnt lgkmcnt(7)
	s_nop 1
	v_mfma_f32_32x32x2_f32 v[174:189], v194, v248, v[174:189]
	v_mfma_f32_32x32x2_f32 v[98:113], v194, v249, v[98:113]
	ds_read_b32 v194, v202 offset:8800
	v_mov_b32_e32 v250, v12
	v_mov_b32_e32 v251, v13
	s_nop 1
	v_permlane32_swap_b32_e32 v250, v251
	s_waitcnt lgkmcnt(7)
	s_nop 1
	v_mfma_f32_32x32x2_f32 v[174:189], v195, v250, v[174:189]
	v_mfma_f32_32x32x2_f32 v[98:113], v195, v251, v[98:113]
	ds_read_b32 v195, v202 offset:8808
	v_mov_b32_e32 v246, v14
	v_mov_b32_e32 v247, v15
	s_nop 1
	v_permlane32_swap_b32_e32 v246, v247
	s_waitcnt lgkmcnt(7)
	s_nop 1
	v_mfma_f32_32x32x2_f32 v[174:189], v196, v246, v[174:189]
	v_mfma_f32_32x32x2_f32 v[98:113], v196, v247, v[98:113]
	ds_read_b32 v196, v202 offset:8816
	v_mov_b32_e32 v248, v16
	v_mov_b32_e32 v249, v17
	s_nop 1
	v_permlane32_swap_b32_e32 v248, v249
	s_waitcnt lgkmcnt(7)
	s_nop 1
	v_mfma_f32_32x32x2_f32 v[174:189], v197, v248, v[174:189]
	v_mfma_f32_32x32x2_f32 v[98:113], v197, v249, v[98:113]
	ds_read_b32 v197, v202 offset:8824
	v_mov_b32_e32 v250, v18
	v_mov_b32_e32 v251, v19
	s_nop 1
	v_permlane32_swap_b32_e32 v250, v251
	s_waitcnt lgkmcnt(7)
	s_nop 1
	v_mfma_f32_32x32x2_f32 v[174:189], v190, v250, v[174:189]
	v_mfma_f32_32x32x2_f32 v[98:113], v190, v251, v[98:113]
	v_mov_b32_e32 v246, v20
	v_mov_b32_e32 v247, v21
	s_nop 1
	v_permlane32_swap_b32_e32 v246, v247
	s_waitcnt lgkmcnt(6)
	s_nop 1
	v_mfma_f32_32x32x2_f32 v[174:189], v191, v246, v[174:189]
	v_mfma_f32_32x32x2_f32 v[98:113], v191, v247, v[98:113]
	v_mov_b32_e32 v248, v22
	v_mov_b32_e32 v249, v23
	s_nop 1
	v_permlane32_swap_b32_e32 v248, v249
	s_waitcnt lgkmcnt(5)
	s_nop 1
	v_mfma_f32_32x32x2_f32 v[174:189], v192, v248, v[174:189]
	v_mfma_f32_32x32x2_f32 v[98:113], v192, v249, v[98:113]
	v_mov_b32_e32 v250, v24
	v_mov_b32_e32 v251, v25
	s_nop 1
	v_permlane32_swap_b32_e32 v250, v251
	s_waitcnt lgkmcnt(4)
	s_nop 1
	v_mfma_f32_32x32x2_f32 v[174:189], v193, v250, v[174:189]
	v_mfma_f32_32x32x2_f32 v[98:113], v193, v251, v[98:113]
	v_mov_b32_e32 v246, v26
	v_mov_b32_e32 v247, v27
	s_nop 1
	v_permlane32_swap_b32_e32 v246, v247
	s_waitcnt lgkmcnt(3)
	s_nop 1
	v_mfma_f32_32x32x2_f32 v[174:189], v194, v246, v[174:189]
	v_mfma_f32_32x32x2_f32 v[98:113], v194, v247, v[98:113]
	v_mov_b32_e32 v248, v28
	v_mov_b32_e32 v249, v29
	s_nop 1
	v_permlane32_swap_b32_e32 v248, v249
	s_waitcnt lgkmcnt(2)
	s_nop 1
	v_mfma_f32_32x32x2_f32 v[174:189], v195, v248, v[174:189]
	v_mfma_f32_32x32x2_f32 v[98:113], v195, v249, v[98:113]
	v_mov_b32_e32 v250, v30
	v_mov_b32_e32 v251, v31
	s_nop 1
	v_permlane32_swap_b32_e32 v250, v251
	s_waitcnt lgkmcnt(1)
	s_nop 1
	v_mfma_f32_32x32x2_f32 v[174:189], v196, v250, v[174:189]
	v_mfma_f32_32x32x2_f32 v[98:113], v196, v251, v[98:113]
	v_mov_b32_e32 v246, v32
	v_mov_b32_e32 v247, v33
	s_nop 1
	v_permlane32_swap_b32_e32 v246, v247
	s_waitcnt lgkmcnt(0)
	s_nop 1
	v_mfma_f32_32x32x2_f32 v[174:189], v197, v246, v[174:189]
	v_mfma_f32_32x32x2_f32 v[98:113], v197, v247, v[98:113]
	s_nop 15
	s_nop 7
	v_permlane32_swap_b32_e32 v174, v98
	v_permlane32_swap_b32_e32 v175, v99
	v_permlane32_swap_b32_e32 v176, v100
	v_permlane32_swap_b32_e32 v177, v101
	v_permlane32_swap_b32_e32 v178, v102
	v_permlane32_swap_b32_e32 v179, v103
	v_permlane32_swap_b32_e32 v180, v104
	v_permlane32_swap_b32_e32 v181, v105
	v_permlane32_swap_b32_e32 v182, v106
	v_permlane32_swap_b32_e32 v183, v107
	v_permlane32_swap_b32_e32 v184, v108
	v_permlane32_swap_b32_e32 v185, v109
	v_permlane32_swap_b32_e32 v186, v110
	v_permlane32_swap_b32_e32 v187, v111
	v_permlane32_swap_b32_e32 v188, v112
	v_permlane32_swap_b32_e32 v189, v113
	v_lshlrev_b32_e32 v59, 16, v59
	v_fma_f32 v34, v204, v59, -v174
	v_mad_u32_u24 v61, v55, 35, v51
	ds_read_u16 v59, v61
	ds_read_b32 v204, v53 offset:140
	ds_read_b128 v[190:193], v57 offset:9920
	v_pk_fma_f32 v[250:251], v[198:199], v[34:35], 0 op_sel_hi:[1,1,0]
	v_pk_fma_f32 v[202:203], v[200:201], v[36:37], 0 op_sel_hi:[1,1,0]
	v_add_f32_e32 v250, v250, v251
	v_add_f32_e32 v202, v202, v203
	v_lshlrev_b32_e32 v221, 16, v221
	v_add_f32_e32 v250, v250, v202
	v_add_f32_e32 v250, v250, v175
	v_fma_f32 v35, v220, v221, -v250
	v_mad_u32_u24 v61, v55, 36, v51
	ds_read_u16 v221, v61
	ds_read_b32 v220, v53 offset:144
	ds_read_b128 v[194:197], v57 offset:10192
	ds_read_b128 v[214:217], v57 offset:10208
	v_pk_fma_f32 v[246:247], v[206:207], v[34:35], 0 op_sel_hi:[1,1,0]
	v_pk_fma_f32 v[248:249], v[208:209], v[36:37], 0 op_sel_hi:[1,1,0]
	v_add_f32_e32 v246, v246, v247
	v_add_f32_e32 v248, v248, v249
	v_lshlrev_b32_e32 v227, 16, v227
	v_add_f32_e32 v246, v246, v248
	v_add_f32_e32 v246, v246, v176
	v_fma_f32 v36, v226, v227, -v246
	v_mad_u32_u24 v61, v55, 37, v51
	ds_read_u16 v227, v61
	ds_read_b32 v226, v53 offset:148
	ds_read_b128 v[238:241], v57 offset:10464
	ds_read_b128 v[242:245], v57 offset:10480
	v_pk_fma_f32 v[250:251], v[210:211], v[34:35], 0 op_sel_hi:[1,1,0]
	v_pk_fma_f32 v[202:203], v[212:213], v[36:37], 0 op_sel_hi:[1,1,0]
	v_add_f32_e32 v250, v250, v251
	v_add_f32_e32 v202, v202, v203
	s_waitcnt lgkmcnt(5)
	v_lshlrev_b32_e32 v59, 16, v59
	v_add_f32_e32 v250, v250, v202
	v_add_f32_e32 v250, v250, v177
	v_fma_f32 v37, v204, v59, -v250
	v_mad_u32_u24 v61, v55, 38, v51
	ds_read_u16 v59, v61
	ds_read_b32 v204, v53 offset:152
	ds_read_b128 v[198:201], v57 offset:10736
	ds_read_b128 v[206:209], v57 offset:10752
	v_pk_fma_f32 v[246:247], v[190:191], v[34:35], 0 op_sel_hi:[1,1,0]
	v_pk_fma_f32 v[248:249], v[192:193], v[36:37], 0 op_sel_hi:[1,1,0]
	v_pk_fma_f32 v[250:251], v[194:195], v[34:35], 0 op_sel_hi:[1,1,0]
	v_pk_fma_f32 v[202:203], v[196:197], v[36:37], 0 op_sel_hi:[1,1,0]
	v_add_f32_e32 v246, v246, v247
	v_add_f32_e32 v248, v248, v249
	v_lshlrev_b32_e32 v221, 16, v221
	v_add_f32_e32 v246, v246, v248
	v_add_f32_e32 v246, v246, v98
	v_fma_f32 v86, v220, v221, -v246
	v_mad_u32_u24 v61, v55, 39, v51
	ds_read_u16 v221, v61
	ds_read_b32 v220, v53 offset:156
	ds_read_b128 v[210:213], v57 offset:11008
	ds_read_b128 v[190:193], v57 offset:11024
	s_waitcnt lgkmcnt(5)
	v_pk_fma_f32 v[250:251], v[214:215], v[86:87], v[250:251]
	v_pk_fma_f32 v[202:203], v[216:217], v[88:89], v[202:203]
	v_pk_fma_f32 v[246:247], v[238:239], v[34:35], 0 op_sel_hi:[1,1,0]
	v_pk_fma_f32 v[248:249], v[240:241], v[36:37], 0 op_sel_hi:[1,1,0]
	v_add_f32_e32 v250, v250, v251
	v_add_f32_e32 v202, v202, v203
	v_lshlrev_b32_e32 v227, 16, v227
	v_add_f32_e32 v250, v250, v202
	v_add_f32_e32 v250, v250, v99
	v_fma_f32 v87, v226, v227, -v250
	v_mad_u32_u24 v61, v55, 40, v51
	ds_read_u16 v227, v61
	ds_read_b32 v226, v53 offset:160
	ds_read_b128 v[194:197], v57 offset:11280
	ds_read_b128 v[214:217], v57 offset:11296
	ds_read_b128 v[238:241], v57 offset:11312
	v_pk_fma_f32 v[246:247], v[242:243], v[86:87], v[246:247]
	v_pk_fma_f32 v[248:249], v[244:245], v[88:89], v[248:249]
	v_pk_fma_f32 v[250:251], v[198:199], v[34:35], 0 op_sel_hi:[1,1,0]
	v_pk_fma_f32 v[202:203], v[200:201], v[36:37], 0 op_sel_hi:[1,1,0]
	v_add_f32_e32 v246, v246, v247
	v_add_f32_e32 v248, v248, v249
	v_lshlrev_b32_e32 v59, 16, v59
	v_add_f32_e32 v246, v246, v248
	v_add_f32_e32 v246, v246, v100
	v_fma_f32 v88, v204, v59, -v246
	v_mad_u32_u24 v61, v55, 41, v51
	ds_read_u16 v59, v61
	ds_read_b32 v204, v53 offset:164
	ds_read_b128 v[242:245], v57 offset:11552
	s_waitcnt lgkmcnt(5)
	v_pk_fma_f32 v[250:251], v[206:207], v[86:87], v[250:251]
	v_pk_fma_f32 v[202:203], v[208:209], v[88:89], v[202:203]
	ds_read_b128 v[198:201], v57 offset:11568
	ds_read_b128 v[206:209], v57 offset:11584
	v_pk_fma_f32 v[246:247], v[210:211], v[34:35], 0 op_sel_hi:[1,1,0]
	v_pk_fma_f32 v[248:249], v[212:213], v[36:37], 0 op_sel_hi:[1,1,0]
	v_add_f32_e32 v250, v250, v251
	v_add_f32_e32 v202, v202, v203
	v_lshlrev_b32_e32 v221, 16, v221
	v_add_f32_e32 v250, v250, v202
	v_add_f32_e32 v250, v250, v101
	v_fma_f32 v89, v220, v221, -v250
	v_mad_u32_u24 v61, v55, 42, v51
	ds_read_u16 v221, v61
	ds_read_b32 v220, v53 offset:168
	ds_read_b128 v[210:213], v57 offset:11824
	v_pk_fma_f32 v[246:247], v[190:191], v[86:87], v[246:247]
	v_pk_fma_f32 v[248:249], v[192:193], v[88:89], v[248:249]
	ds_read_b128 v[190:193], v57 offset:11840
	v_pk_fma_f32 v[250:251], v[194:195], v[34:35], 0 op_sel_hi:[1,1,0]
	v_pk_fma_f32 v[202:203], v[196:197], v[36:37], 0 op_sel_hi:[1,1,0]
	ds_read_b128 v[194:197], v57 offset:11856
	v_add_f32_e32 v246, v246, v247
	s_waitcnt lgkmcnt(5)
	v_pk_fma_f32 v[250:251], v[214:215], v[86:87], v[250:251]
	v_pk_fma_f32 v[202:203], v[216:217], v[88:89], v[202:203]
	v_add_f32_e32 v248, v248, v249
	v_lshlrev_b32_e32 v227, 16, v227
	v_add_f32_e32 v246, v246, v248
	v_add_f32_e32 v246, v246, v178
	v_fma_f32 v90, v226, v227, -v246
	v_mad_u32_u24 v61, v55, 43, v51
	ds_read_u16 v227, v61
	ds_read_b32 v226, v53 offset:172
	ds_read_b128 v[214:217], v57 offset:12096
	v_pk_fma_f32 v[250:251], v[238:239], v[90:91], v[250:251]
	v_pk_fma_f32 v[202:203], v[240:241], v[92:93], v[202:203]
	ds_read_b128 v[238:241], v57 offset:12112
	v_pk_fma_f32 v[246:247], v[242:243], v[34:35], 0 op_sel_hi:[1,1,0]
	v_pk_fma_f32 v[248:249], v[244:245], v[36:37], 0 op_sel_hi:[1,1,0]
	ds_read_b128 v[242:245], v57 offset:12128
	v_add_f32_e32 v250, v250, v251
	v_pk_fma_f32 v[246:247], v[198:199], v[86:87], v[246:247]
	v_pk_fma_f32 v[248:249], v[200:201], v[88:89], v[248:249]
	v_add_f32_e32 v202, v202, v203
	v_lshlrev_b32_e32 v59, 16, v59
	v_add_f32_e32 v250, v250, v202
	v_add_f32_e32 v250, v250, v179
	v_fma_f32 v91, v204, v59, -v250
	v_mad_u32_u24 v61, v55, 44, v51
	ds_read_u16 v59, v61
	ds_read_b32 v204, v53 offset:176
	ds_read_b128 v[198:201], v57 offset:12368
	v_pk_fma_f32 v[246:247], v[206:207], v[90:91], v[246:247]
	v_pk_fma_f32 v[248:249], v[208:209], v[92:93], v[248:249]
	s_waitcnt lgkmcnt(5)
	v_pk_fma_f32 v[250:251], v[210:211], v[34:35], 0 op_sel_hi:[1,1,0]
	v_pk_fma_f32 v[202:203], v[212:213], v[36:37], 0 op_sel_hi:[1,1,0]
	ds_read_b128 v[206:209], v57 offset:12384
	ds_read_b128 v[210:213], v57 offset:12400
	v_add_f32_e32 v246, v246, v247
	v_pk_fma_f32 v[250:251], v[190:191], v[86:87], v[250:251]
	v_pk_fma_f32 v[202:203], v[192:193], v[88:89], v[202:203]
	ds_read_b128 v[190:193], v57 offset:12416
	v_add_f32_e32 v248, v248, v249
	v_lshlrev_b32_e32 v221, 16, v221
	v_add_f32_e32 v246, v246, v248
	v_add_f32_e32 v246, v246, v180
	v_fma_f32 v92, v220, v221, -v246
	v_mad_u32_u24 v61, v55, 45, v51
	ds_read_u16 v221, v61
	ds_read_b32 v220, v53 offset:180
	v_pk_fma_f32 v[250:251], v[194:195], v[90:91], v[250:251]
	v_pk_fma_f32 v[202:203], v[196:197], v[92:93], v[202:203]
	ds_read_b128 v[194:197], v57 offset:12640
	v_pk_fma_f32 v[246:247], v[214:215], v[34:35], 0 op_sel_hi:[1,1,0]
	v_pk_fma_f32 v[248:249], v[216:217], v[36:37], 0 op_sel_hi:[1,1,0]
	ds_read_b128 v[214:217], v57 offset:12656
	v_add_f32_e32 v250, v250, v251
	s_waitcnt lgkmcnt(5)
	v_pk_fma_f32 v[246:247], v[238:239], v[86:87], v[246:247]
	v_pk_fma_f32 v[248:249], v[240:241], v[88:89], v[248:249]
	ds_read_b128 v[238:241], v57 offset:12672
	v_add_f32_e32 v202, v202, v203
	v_lshlrev_b32_e32 v227, 16, v227
	v_add_f32_e32 v250, v250, v202
	v_add_f32_e32 v250, v250, v181
	v_fma_f32 v93, v226, v227, -v250
	v_pk_fma_f32 v[246:247], v[242:243], v[90:91], v[246:247]
	v_pk_fma_f32 v[248:249], v[244:245], v[92:93], v[248:249]
	ds_read_b128 v[242:245], v57 offset:12688
	v_mad_u32_u24 v61, v55, 46, v51
	ds_read_u16 v227, v61
	ds_read_b32 v226, v53 offset:184
	v_pk_fma_f32 v[250:251], v[198:199], v[34:35], 0 op_sel_hi:[1,1,0]
	v_pk_fma_f32 v[202:203], v[200:201], v[36:37], 0 op_sel_hi:[1,1,0]
	ds_read_b128 v[198:201], v57 offset:12912
	v_add_f32_e32 v246, v246, v247
	v_pk_fma_f32 v[250:251], v[206:207], v[86:87], v[250:251]
	v_pk_fma_f32 v[202:203], v[208:209], v[88:89], v[202:203]
	ds_read_b128 v[206:209], v57 offset:12928
	v_add_f32_e32 v248, v248, v249
	v_pk_fma_f32 v[250:251], v[210:211], v[90:91], v[250:251]
	v_pk_fma_f32 v[202:203], v[212:213], v[92:93], v[202:203]
	ds_read_b128 v[210:213], v57 offset:12944
	v_lshlrev_b32_e32 v59, 16, v59
	v_add_f32_e32 v246, v246, v248
	v_add_f32_e32 v246, v246, v102
	v_fma_f32 v94, v204, v59, -v246
	s_waitcnt lgkmcnt(5)
	v_pk_fma_f32 v[250:251], v[190:191], v[94:95], v[250:251]
	v_pk_fma_f32 v[202:203], v[192:193], v[96:97], v[202:203]
	ds_read_b128 v[190:193], v57 offset:12960
	v_mad_u32_u24 v61, v55, 47, v51
	ds_read_u16 v59, v61
	ds_read_b32 v204, v53 offset:188
	v_pk_fma_f32 v[246:247], v[194:195], v[34:35], 0 op_sel_hi:[1,1,0]
	v_pk_fma_f32 v[248:249], v[196:197], v[36:37], 0 op_sel_hi:[1,1,0]
	ds_read_b128 v[194:197], v57 offset:13184
	v_add_f32_e32 v250, v250, v251
	v_pk_fma_f32 v[246:247], v[214:215], v[86:87], v[246:247]
	v_pk_fma_f32 v[248:249], v[216:217], v[88:89], v[248:249]
	ds_read_b128 v[214:217], v57 offset:13200
	v_add_f32_e32 v202, v202, v203
	v_pk_fma_f32 v[246:247], v[238:239], v[90:91], v[246:247]
	v_pk_fma_f32 v[248:249], v[240:241], v[92:93], v[248:249]
	ds_read_b128 v[238:241], v57 offset:13216
	v_lshlrev_b32_e32 v221, 16, v221
	v_add_f32_e32 v250, v250, v202
	v_add_f32_e32 v250, v250, v103
	v_fma_f32 v95, v220, v221, -v250
	v_pk_fma_f32 v[246:247], v[242:243], v[94:95], v[246:247]
	v_pk_fma_f32 v[248:249], v[244:245], v[96:97], v[248:249]
	ds_read_b128 v[242:245], v57 offset:13232
	s_waitcnt lgkmcnt(5)
	v_pk_fma_f32 v[250:251], v[198:199], v[34:35], 0 op_sel_hi:[1,1,0]
	v_pk_fma_f32 v[202:203], v[200:201], v[36:37], 0 op_sel_hi:[1,1,0]
	v_mad_u32_u24 v61, v55, 48, v51
	ds_read_u16 v221, v61
	ds_read_b32 v220, v53 offset:192
	ds_read_b128 v[198:201], v57 offset:13456
	v_add_f32_e32 v246, v246, v247
	v_pk_fma_f32 v[250:251], v[206:207], v[86:87], v[250:251]
	v_pk_fma_f32 v[202:203], v[208:209], v[88:89], v[202:203]
	ds_read_b128 v[206:209], v57 offset:13472
	v_add_f32_e32 v248, v248, v249
	v_pk_fma_f32 v[250:251], v[210:211], v[90:91], v[250:251]
	v_pk_fma_f32 v[202:203], v[212:213], v[92:93], v[202:203]
	ds_read_b128 v[210:213], v57 offset:13488
	v_lshlrev_b32_e32 v227, 16, v227
	v_add_f32_e32 v246, v246, v248
	v_add_f32_e32 v246, v246, v104
	v_fma_f32 v96, v226, v227, -v246
	v_pk_fma_f32 v[250:251], v[190:191], v[94:95], v[250:251]
	v_pk_fma_f32 v[202:203], v[192:193], v[96:97], v[202:203]
	ds_read_b128 v[190:193], v57 offset:13504
	s_waitcnt lgkmcnt(5)
	v_pk_fma_f32 v[246:247], v[194:195], v[34:35], 0 op_sel_hi:[1,1,0]
	v_pk_fma_f32 v[248:249], v[196:197], v[36:37], 0 op_sel_hi:[1,1,0]
	ds_read_b128 v[194:197], v57 offset:13520
	v_mad_u32_u24 v61, v55, 49, v51
	ds_read_u16 v227, v61
	ds_read_b32 v226, v53 offset:196
	v_add_f32_e32 v250, v250, v251
	v_pk_fma_f32 v[246:247], v[214:215], v[86:87], v[246:247]
	v_pk_fma_f32 v[248:249], v[216:217], v[88:89], v[248:249]
	ds_read_b128 v[214:217], v57 offset:13728
	v_add_f32_e32 v202, v202, v203
	v_pk_fma_f32 v[246:247], v[238:239], v[90:91], v[246:247]
	v_pk_fma_f32 v[248:249], v[240:241], v[92:93], v[248:249]
	ds_read_b128 v[238:241], v57 offset:13744
	v_lshlrev_b32_e32 v59, 16, v59
	v_add_f32_e32 v250, v250, v202
	v_add_f32_e32 v250, v250, v105
	v_fma_f32 v97, v204, v59, -v250
	v_pk_fma_f32 v[246:247], v[242:243], v[94:95], v[246:247]
	v_pk_fma_f32 v[248:249], v[244:245], v[96:97], v[248:249]
	ds_read_b128 v[242:245], v57 offset:13760
	s_waitcnt lgkmcnt(5)
	v_pk_fma_f32 v[250:251], v[198:199], v[34:35], 0 op_sel_hi:[1,1,0]
	v_pk_fma_f32 v[202:203], v[200:201], v[36:37], 0 op_sel_hi:[1,1,0]
	ds_read_b128 v[198:201], v57 offset:13776
	v_add_f32_e32 v246, v246, v247
	v_pk_fma_f32 v[250:251], v[206:207], v[86:87], v[250:251]
	v_pk_fma_f32 v[202:203], v[208:209], v[88:89], v[202:203]
	ds_read_b128 v[206:209], v57 offset:13792
	v_mad_u32_u24 v61, v55, 50, v51
	ds_read_u16 v59, v61
	ds_read_b32 v204, v53 offset:200
	v_add_f32_e32 v248, v248, v249
	v_pk_fma_f32 v[250:251], v[210:211], v[90:91], v[250:251]
	v_pk_fma_f32 v[202:203], v[212:213], v[92:93], v[202:203]
	ds_read_b128 v[210:213], v57 offset:14000
	v_lshlrev_b32_e32 v221, 16, v221
	v_pk_fma_f32 v[250:251], v[190:191], v[94:95], v[250:251]
	v_pk_fma_f32 v[202:203], v[192:193], v[96:97], v[202:203]
	ds_read_b128 v[190:193], v57 offset:14016
	v_add_f32_e32 v246, v246, v248
	v_add_f32_e32 v246, v246, v182
	v_fma_f32 v98, v220, v221, -v246
	v_pk_fma_f32 v[250:251], v[194:195], v[98:99], v[250:251]
	v_pk_fma_f32 v[202:203], v[196:197], v[100:101], v[202:203]
	ds_read_b128 v[194:197], v57 offset:14032
	s_waitcnt lgkmcnt(5)
	v_pk_fma_f32 v[246:247], v[214:215], v[34:35], 0 op_sel_hi:[1,1,0]
	v_pk_fma_f32 v[248:249], v[216:217], v[36:37], 0 op_sel_hi:[1,1,0]
	ds_read_b128 v[214:217], v57 offset:14048
	v_add_f32_e32 v250, v250, v251
	v_pk_fma_f32 v[246:247], v[238:239], v[86:87], v[246:247]
	v_pk_fma_f32 v[248:249], v[240:241], v[88:89], v[248:249]
	ds_read_b128 v[238:241], v57 offset:14064
	v_mad_u32_u24 v61, v55, 51, v51
	ds_read_u16 v221, v61
	ds_read_b32 v220, v53 offset:204
	v_add_f32_e32 v202, v202, v203
	v_pk_fma_f32 v[246:247], v[242:243], v[90:91], v[246:247]
	v_pk_fma_f32 v[248:249], v[244:245], v[92:93], v[248:249]
	ds_read_b128 v[242:245], v57 offset:14272
	v_lshlrev_b32_e32 v227, 16, v227
	v_pk_fma_f32 v[246:247], v[198:199], v[94:95], v[246:247]
	v_pk_fma_f32 v[248:249], v[200:201], v[96:97], v[248:249]
	ds_read_b128 v[198:201], v57 offset:14288
	v_add_f32_e32 v250, v250, v202
	v_add_f32_e32 v250, v250, v183
	v_fma_f32 v99, v226, v227, -v250
	v_pk_fma_f32 v[246:247], v[206:207], v[98:99], v[246:247]
	v_pk_fma_f32 v[248:249], v[208:209], v[100:101], v[248:249]
	ds_read_b128 v[206:209], v57 offset:14304
	s_waitcnt lgkmcnt(5)
	v_pk_fma_f32 v[250:251], v[210:211], v[34:35], 0 op_sel_hi:[1,1,0]
	v_pk_fma_f32 v[202:203], v[212:213], v[36:37], 0 op_sel_hi:[1,1,0]
	ds_read_b128 v[210:213], v57 offset:14320
	v_add_f32_e32 v246, v246, v247
	v_pk_fma_f32 v[250:251], v[190:191], v[86:87], v[250:251]
	v_pk_fma_f32 v[202:203], v[192:193], v[88:89], v[202:203]
	ds_read_b128 v[190:193], v57 offset:14336
	v_mad_u32_u24 v61, v55, 52, v51
	ds_read_u16 v227, v61
	ds_read_b32 v226, v53 offset:208
	v_add_f32_e32 v248, v248, v249
	v_pk_fma_f32 v[250:251], v[194:195], v[90:91], v[250:251]
	v_pk_fma_f32 v[202:203], v[196:197], v[92:93], v[202:203]
	ds_read_b128 v[194:197], v57 offset:14544
	v_lshlrev_b32_e32 v59, 16, v59
	v_pk_fma_f32 v[250:251], v[214:215], v[94:95], v[250:251]
	v_pk_fma_f32 v[202:203], v[216:217], v[96:97], v[202:203]
	ds_read_b128 v[214:217], v57 offset:14560
	v_add_f32_e32 v246, v246, v248
	v_add_f32_e32 v246, v246, v184
	v_fma_f32 v100, v204, v59, -v246
	v_pk_fma_f32 v[250:251], v[238:239], v[98:99], v[250:251]
	v_pk_fma_f32 v[202:203], v[240:241], v[100:101], v[202:203]
	ds_read_b128 v[238:241], v57 offset:14576
	s_waitcnt lgkmcnt(5)
	v_pk_fma_f32 v[246:247], v[242:243], v[34:35], 0 op_sel_hi:[1,1,0]
	v_pk_fma_f32 v[248:249], v[244:245], v[36:37], 0 op_sel_hi:[1,1,0]
	ds_read_b128 v[242:245], v57 offset:14592
	v_add_f32_e32 v250, v250, v251
	v_pk_fma_f32 v[246:247], v[198:199], v[86:87], v[246:247]
	v_pk_fma_f32 v[248:249], v[200:201], v[88:89], v[248:249]
	ds_read_b128 v[198:201], v57 offset:14608
	v_add_f32_e32 v202, v202, v203
	v_pk_fma_f32 v[246:247], v[206:207], v[90:91], v[246:247]
	v_pk_fma_f32 v[248:249], v[208:209], v[92:93], v[248:249]
	ds_read_b128 v[206:209], v57 offset:14624
	v_mad_u32_u24 v61, v55, 53, v51
	ds_read_u16 v59, v61
	ds_read_b32 v204, v53 offset:212
	v_lshlrev_b32_e32 v221, 16, v221
	v_pk_fma_f32 v[246:247], v[210:211], v[94:95], v[246:247]
	v_pk_fma_f32 v[248:249], v[212:213], v[96:97], v[248:249]
	ds_read_b128 v[210:213], v57 offset:14816
	v_add_f32_e32 v250, v250, v202
	v_add_f32_e32 v250, v250, v185
	v_fma_f32 v101, v220, v221, -v250
	v_pk_fma_f32 v[246:247], v[190:191], v[98:99], v[246:247]
	v_pk_fma_f32 v[248:249], v[192:193], v[100:101], v[248:249]
	ds_read_b128 v[190:193], v57 offset:14832
	s_waitcnt lgkmcnt(5)
	v_pk_fma_f32 v[250:251], v[194:195], v[34:35], 0 op_sel_hi:[1,1,0]
	v_pk_fma_f32 v[202:203], v[196:197], v[36:37], 0 op_sel_hi:[1,1,0]
	ds_read_b128 v[194:197], v57 offset:14848
	v_add_f32_e32 v246, v246, v247
	v_pk_fma_f32 v[250:251], v[214:215], v[86:87], v[250:251]
	v_pk_fma_f32 v[202:203], v[216:217], v[88:89], v[202:203]
	ds_read_b128 v[214:217], v57 offset:14864
	v_add_f32_e32 v248, v248, v249
	v_pk_fma_f32 v[250:251], v[238:239], v[90:91], v[250:251]
	v_pk_fma_f32 v[202:203], v[240:241], v[92:93], v[202:203]
	ds_read_b128 v[238:241], v57 offset:14880
	v_lshlrev_b32_e32 v227, 16, v227
	v_pk_fma_f32 v[250:251], v[242:243], v[94:95], v[250:251]
	v_pk_fma_f32 v[202:203], v[244:245], v[96:97], v[202:203]
	ds_read_b128 v[242:245], v57 offset:14896
	v_mad_u32_u24 v61, v55, 54, v51
	ds_read_u16 v221, v61
	ds_read_b32 v220, v53 offset:216
	v_add_f32_e32 v246, v246, v248
	v_pk_fma_f32 v[250:251], v[198:199], v[98:99], v[250:251]
	v_pk_fma_f32 v[202:203], v[200:201], v[100:101], v[202:203]
	ds_read_b128 v[198:201], v57 offset:15088
	v_add_f32_e32 v246, v246, v106
	v_fma_f32 v102, v226, v227, -v246
	s_waitcnt lgkmcnt(5)
	v_pk_fma_f32 v[250:251], v[206:207], v[102:103], v[250:251]
	v_pk_fma_f32 v[202:203], v[208:209], v[104:105], v[202:203]
	ds_read_b128 v[206:209], v57 offset:15104
	v_pk_fma_f32 v[246:247], v[210:211], v[34:35], 0 op_sel_hi:[1,1,0]
	v_pk_fma_f32 v[248:249], v[212:213], v[36:37], 0 op_sel_hi:[1,1,0]
	ds_read_b128 v[210:213], v57 offset:15120
	v_add_f32_e32 v250, v250, v251
	v_pk_fma_f32 v[246:247], v[190:191], v[86:87], v[246:247]
	v_pk_fma_f32 v[248:249], v[192:193], v[88:89], v[248:249]
	ds_read_b128 v[190:193], v57 offset:15136
	v_add_f32_e32 v202, v202, v203
	v_pk_fma_f32 v[246:247], v[194:195], v[90:91], v[246:247]
	v_pk_fma_f32 v[248:249], v[196:197], v[92:93], v[248:249]
	ds_read_b128 v[194:197], v57 offset:15152
	v_lshlrev_b32_e32 v59, 16, v59
	v_pk_fma_f32 v[246:247], v[214:215], v[94:95], v[246:247]
	v_pk_fma_f32 v[248:249], v[216:217], v[96:97], v[248:249]
	ds_read_b128 v[214:217], v57 offset:15168
	v_mad_u32_u24 v61, v55, 55, v51
	ds_read_u16 v227, v61
	ds_read_b32 v226, v53 offset:220
	v_add_f32_e32 v250, v250, v202
	s_waitcnt lgkmcnt(5)
	v_pk_fma_f32 v[246:247], v[238:239], v[98:99], v[246:247]
	v_pk_fma_f32 v[248:249], v[240:241], v[100:101], v[248:249]
	ds_read_b128 v[238:241], v57 offset:15360
	v_add_f32_e32 v250, v250, v107
	v_fma_f32 v103, v204, v59, -v250
	v_pk_fma_f32 v[246:247], v[242:243], v[102:103], v[246:247]
	v_pk_fma_f32 v[248:249], v[244:245], v[104:105], v[248:249]
	ds_read_b128 v[242:245], v57 offset:15376
	v_pk_fma_f32 v[250:251], v[198:199], v[34:35], 0 op_sel_hi:[1,1,0]
	v_pk_fma_f32 v[202:203], v[200:201], v[36:37], 0 op_sel_hi:[1,1,0]
	ds_read_b128 v[198:201], v57 offset:15392
	v_add_f32_e32 v246, v246, v247
	v_pk_fma_f32 v[250:251], v[206:207], v[86:87], v[250:251]
	v_pk_fma_f32 v[202:203], v[208:209], v[88:89], v[202:203]
	ds_read_b128 v[206:209], v57 offset:15408
	v_add_f32_e32 v248, v248, v249
	v_pk_fma_f32 v[250:251], v[210:211], v[90:91], v[250:251]
	v_pk_fma_f32 v[202:203], v[212:213], v[92:93], v[202:203]
	ds_read_b128 v[210:213], v57 offset:15424
	v_lshlrev_b32_e32 v221, 16, v221
	s_waitcnt lgkmcnt(5)
	v_pk_fma_f32 v[250:251], v[190:191], v[94:95], v[250:251]
	v_pk_fma_f32 v[202:203], v[192:193], v[96:97], v[202:203]
	ds_read_b128 v[190:193], v57 offset:15440
	v_mad_u32_u24 v61, v55, 56, v51
	ds_read_u16 v59, v61
	ds_read_b32 v204, v53 offset:224
	v_add_f32_e32 v246, v246, v248
	v_pk_fma_f32 v[250:251], v[194:195], v[98:99], v[250:251]
	v_pk_fma_f32 v[202:203], v[196:197], v[100:101], v[202:203]
	ds_read_b128 v[194:197], v57 offset:15632
	v_add_f32_e32 v246, v246, v108
	v_fma_f32 v104, v220, v221, -v246
	v_pk_fma_f32 v[250:251], v[214:215], v[102:103], v[250:251]
	v_pk_fma_f32 v[202:203], v[216:217], v[104:105], v[202:203]
	ds_read_b128 v[214:217], v57 offset:15648
	s_waitcnt lgkmcnt(5)
	v_pk_fma_f32 v[246:247], v[238:239], v[34:35], 0 op_sel_hi:[1,1,0]
	v_pk_fma_f32 v[248:249], v[240:241], v[36:37], 0 op_sel_hi:[1,1,0]
	ds_read_b128 v[238:241], v57 offset:15664
	v_add_f32_e32 v250, v250, v251
	v_pk_fma_f32 v[246:247], v[242:243], v[86:87], v[246:247]
	v_pk_fma_f32 v[248:249], v[244:245], v[88:89], v[248:249]
	ds_read_b128 v[242:245], v57 offset:15680
	v_add_f32_e32 v202, v202, v203
	v_pk_fma_f32 v[246:247], v[198:199], v[90:91], v[246:247]
	v_pk_fma_f32 v[248:249], v[200:201], v[92:93], v[248:249]
	ds_read_b128 v[198:201], v57 offset:15696
	v_lshlrev_b32_e32 v227, 16, v227
	v_pk_fma_f32 v[246:247], v[206:207], v[94:95], v[246:247]
	v_pk_fma_f32 v[248:249], v[208:209], v[96:97], v[248:249]
	ds_read_b128 v[206:209], v57 offset:15712
	v_add_f32_e32 v250, v250, v202
	v_pk_fma_f32 v[246:247], v[210:211], v[98:99], v[246:247]
	v_pk_fma_f32 v[248:249], v[212:213], v[100:101], v[248:249]
	ds_read_b128 v[210:213], v57 offset:15728
	v_mad_u32_u24 v61, v55, 57, v51
	ds_read_u16 v221, v61
	ds_read_b32 v220, v53 offset:228
	v_add_f32_e32 v250, v250, v109
	v_fma_f32 v105, v226, v227, -v250
	s_waitcnt lgkmcnt(5)
	v_pk_fma_f32 v[246:247], v[190:191], v[102:103], v[246:247]
	v_pk_fma_f32 v[248:249], v[192:193], v[104:105], v[248:249]
	ds_read_b128 v[190:193], v57 offset:15904
	v_pk_fma_f32 v[250:251], v[194:195], v[34:35], 0 op_sel_hi:[1,1,0]
	v_pk_fma_f32 v[202:203], v[196:197], v[36:37], 0 op_sel_hi:[1,1,0]
	ds_read_b128 v[194:197], v57 offset:15920
	v_add_f32_e32 v246, v246, v247
	v_pk_fma_f32 v[250:251], v[214:215], v[86:87], v[250:251]
	v_pk_fma_f32 v[202:203], v[216:217], v[88:89], v[202:203]
	ds_read_b128 v[214:217], v57 offset:15936
	v_add_f32_e32 v248, v248, v249
	v_pk_fma_f32 v[250:251], v[238:239], v[90:91], v[250:251]
	v_pk_fma_f32 v[202:203], v[240:241], v[92:93], v[202:203]
	ds_read_b128 v[238:241], v57 offset:15952
	v_lshlrev_b32_e32 v59, 16, v59
	v_pk_fma_f32 v[250:251], v[242:243], v[94:95], v[250:251]
	v_pk_fma_f32 v[202:203], v[244:245], v[96:97], v[202:203]
	ds_read_b128 v[242:245], v57 offset:15968
	v_add_f32_e32 v246, v246, v248
	s_waitcnt lgkmcnt(5)
	v_pk_fma_f32 v[250:251], v[198:199], v[98:99], v[250:251]
	v_pk_fma_f32 v[202:203], v[200:201], v[100:101], v[202:203]
	ds_read_b128 v[198:201], v57 offset:15984
	v_add_f32_e32 v246, v246, v186
	v_pk_fma_f32 v[250:251], v[206:207], v[102:103], v[250:251]
	v_pk_fma_f32 v[202:203], v[208:209], v[104:105], v[202:203]
	ds_read_b128 v[206:209], v57 offset:16000
	v_mad_u32_u24 v61, v55, 58, v51
	ds_read_u16 v227, v61
	ds_read_b32 v226, v53 offset:232
	v_fma_f32 v106, v204, v59, -v246
	v_pk_fma_f32 v[250:251], v[210:211], v[106:107], v[250:251]
	v_pk_fma_f32 v[202:203], v[212:213], v[108:109], v[202:203]
	ds_read_b128 v[210:213], v57 offset:16176
	s_waitcnt lgkmcnt(5)
	v_pk_fma_f32 v[246:247], v[190:191], v[34:35], 0 op_sel_hi:[1,1,0]
	v_pk_fma_f32 v[248:249], v[192:193], v[36:37], 0 op_sel_hi:[1,1,0]
	ds_read_b128 v[190:193], v57 offset:16192
	v_add_f32_e32 v250, v250, v251
	v_pk_fma_f32 v[246:247], v[194:195], v[86:87], v[246:247]
	v_pk_fma_f32 v[248:249], v[196:197], v[88:89], v[248:249]
	ds_read_b128 v[194:197], v57 offset:16208
	v_add_f32_e32 v202, v202, v203
	v_pk_fma_f32 v[246:247], v[214:215], v[90:91], v[246:247]
	v_pk_fma_f32 v[248:249], v[216:217], v[92:93], v[248:249]
	ds_read_b128 v[214:217], v57 offset:16224
	v_lshlrev_b32_e32 v221, 16, v221
	v_pk_fma_f32 v[246:247], v[238:239], v[94:95], v[246:247]
	v_pk_fma_f32 v[248:249], v[240:241], v[96:97], v[248:249]
	ds_read_b128 v[238:241], v57 offset:16240
	v_add_f32_e32 v250, v250, v202
	v_pk_fma_f32 v[246:247], v[242:243], v[98:99], v[246:247]
	v_pk_fma_f32 v[248:249], v[244:245], v[100:101], v[248:249]
	ds_read_b128 v[242:245], v57 offset:16256
	v_add_f32_e32 v250, v250, v187
	s_waitcnt lgkmcnt(5)
	v_pk_fma_f32 v[246:247], v[198:199], v[102:103], v[246:247]
	v_pk_fma_f32 v[248:249], v[200:201], v[104:105], v[248:249]
	ds_read_b128 v[198:201], v57 offset:16272
	v_mad_u32_u24 v61, v55, 59, v51
	ds_read_u16 v59, v61
	ds_read_b32 v204, v53 offset:236
	v_fma_f32 v107, v220, v221, -v250
	v_pk_fma_f32 v[246:247], v[206:207], v[106:107], v[246:247]
	v_pk_fma_f32 v[248:249], v[208:209], v[108:109], v[248:249]
	ds_read_b128 v[206:209], v57 offset:16448
	v_pk_fma_f32 v[250:251], v[210:211], v[34:35], 0 op_sel_hi:[1,1,0]
	v_pk_fma_f32 v[202:203], v[212:213], v[36:37], 0 op_sel_hi:[1,1,0]
	ds_read_b128 v[210:213], v57 offset:16464
	v_add_f32_e32 v246, v246, v247
	s_waitcnt lgkmcnt(5)
	v_pk_fma_f32 v[250:251], v[190:191], v[86:87], v[250:251]
	v_pk_fma_f32 v[202:203], v[192:193], v[88:89], v[202:203]
	ds_read_b128 v[190:193], v57 offset:16480
	v_add_f32_e32 v248, v248, v249
	v_pk_fma_f32 v[250:251], v[194:195], v[90:91], v[250:251]
	v_pk_fma_f32 v[202:203], v[196:197], v[92:93], v[202:203]
	ds_read_b128 v[194:197], v57 offset:16496
	v_lshlrev_b32_e32 v227, 16, v227
	v_pk_fma_f32 v[250:251], v[214:215], v[94:95], v[250:251]
	v_pk_fma_f32 v[202:203], v[216:217], v[96:97], v[202:203]
	ds_read_b128 v[214:217], v57 offset:16512
	v_add_f32_e32 v246, v246, v248
	v_pk_fma_f32 v[250:251], v[238:239], v[98:99], v[250:251]
	v_pk_fma_f32 v[202:203], v[240:241], v[100:101], v[202:203]
	ds_read_b128 v[238:241], v57 offset:16528
	v_add_f32_e32 v246, v246, v188
	v_pk_fma_f32 v[250:251], v[242:243], v[102:103], v[250:251]
	v_pk_fma_f32 v[202:203], v[244:245], v[104:105], v[202:203]
	ds_read_b128 v[242:245], v57 offset:16544
	v_mad_u32_u24 v61, v55, 60, v51
	ds_read_u16 v221, v61
	ds_read_b32 v220, v53 offset:240
	v_fma_f32 v108, v226, v227, -v246
	s_waitcnt lgkmcnt(5)
	v_pk_fma_f32 v[250:251], v[198:199], v[106:107], v[250:251]
	v_pk_fma_f32 v[202:203], v[200:201], v[108:109], v[202:203]
	ds_read_b128 v[198:201], v57 offset:16720
	v_pk_fma_f32 v[246:247], v[206:207], v[34:35], 0 op_sel_hi:[1,1,0]
	v_pk_fma_f32 v[248:249], v[208:209], v[36:37], 0 op_sel_hi:[1,1,0]
	ds_read_b128 v[206:209], v57 offset:16736
	v_add_f32_e32 v250, v250, v251
	v_pk_fma_f32 v[246:247], v[210:211], v[86:87], v[246:247]
	v_pk_fma_f32 v[248:249], v[212:213], v[88:89], v[248:249]
	ds_read_b128 v[210:213], v57 offset:16752
	v_add_f32_e32 v202, v202, v203
	v_pk_fma_f32 v[246:247], v[190:191], v[90:91], v[246:247]
	v_pk_fma_f32 v[248:249], v[192:193], v[92:93], v[248:249]
	ds_read_b128 v[190:193], v57 offset:16768
	v_lshlrev_b32_e32 v59, 16, v59
	v_pk_fma_f32 v[246:247], v[194:195], v[94:95], v[246:247]
	v_pk_fma_f32 v[248:249], v[196:197], v[96:97], v[248:249]
	ds_read_b128 v[194:197], v57 offset:16784
	v_add_f32_e32 v250, v250, v202
	s_waitcnt lgkmcnt(5)
	v_pk_fma_f32 v[246:247], v[214:215], v[98:99], v[246:247]
	v_pk_fma_f32 v[248:249], v[216:217], v[100:101], v[248:249]
	ds_read_b128 v[214:217], v57 offset:16800
	v_add_f32_e32 v250, v250, v189
	v_pk_fma_f32 v[246:247], v[238:239], v[102:103], v[246:247]
	v_pk_fma_f32 v[248:249], v[240:241], v[104:105], v[248:249]
	ds_read_b128 v[238:241], v57 offset:16816
	v_fma_f32 v109, v204, v59, -v250
	v_pk_fma_f32 v[246:247], v[242:243], v[106:107], v[246:247]
	v_pk_fma_f32 v[248:249], v[244:245], v[108:109], v[248:249]
	ds_read_b128 v[242:245], v57 offset:16832
	v_mad_u32_u24 v61, v55, 61, v51
	ds_read_u16 v227, v61
	ds_read_b32 v226, v53 offset:244
	s_waitcnt lgkmcnt(5)
	v_pk_fma_f32 v[250:251], v[198:199], v[34:35], 0 op_sel_hi:[1,1,0]
	v_pk_fma_f32 v[202:203], v[200:201], v[36:37], 0 op_sel_hi:[1,1,0]
	ds_read_b128 v[198:201], v57 offset:16992
	v_add_f32_e32 v246, v246, v247
	v_pk_fma_f32 v[250:251], v[206:207], v[86:87], v[250:251]
	v_pk_fma_f32 v[202:203], v[208:209], v[88:89], v[202:203]
	ds_read_b128 v[206:209], v57 offset:17008
	v_add_f32_e32 v248, v248, v249
	v_pk_fma_f32 v[250:251], v[210:211], v[90:91], v[250:251]
	v_pk_fma_f32 v[202:203], v[212:213], v[92:93], v[202:203]
	ds_read_b128 v[210:213], v57 offset:17024
	v_lshlrev_b32_e32 v221, 16, v221
	v_pk_fma_f32 v[250:251], v[190:191], v[94:95], v[250:251]
	v_pk_fma_f32 v[202:203], v[192:193], v[96:97], v[202:203]
	ds_read_b128 v[190:193], v57 offset:17040
	v_add_f32_e32 v246, v246, v248
	v_pk_fma_f32 v[250:251], v[194:195], v[98:99], v[250:251]
	v_pk_fma_f32 v[202:203], v[196:197], v[100:101], v[202:203]
	ds_read_b128 v[194:197], v57 offset:17056
	v_add_f32_e32 v246, v246, v110
	s_waitcnt lgkmcnt(5)
	v_pk_fma_f32 v[250:251], v[214:215], v[102:103], v[250:251]
	v_pk_fma_f32 v[202:203], v[216:217], v[104:105], v[202:203]
	ds_read_b128 v[214:217], v57 offset:17072
	v_fma_f32 v110, v220, v221, -v246
	v_pk_fma_f32 v[250:251], v[238:239], v[106:107], v[250:251]
	v_pk_fma_f32 v[202:203], v[240:241], v[108:109], v[202:203]
	ds_read_b128 v[238:241], v57 offset:17088
	v_pk_fma_f32 v[250:251], v[242:243], v[110:111], v[250:251]
	v_pk_fma_f32 v[202:203], v[244:245], v[112:113], v[202:203]
	ds_read_b128 v[242:245], v57 offset:17104
	v_mad_u32_u24 v61, v55, 62, v51
	ds_read_u16 v59, v61
	ds_read_b32 v204, v53 offset:248
	s_waitcnt lgkmcnt(5)
	v_pk_fma_f32 v[246:247], v[198:199], v[34:35], 0 op_sel_hi:[1,1,0]
	v_pk_fma_f32 v[248:249], v[200:201], v[36:37], 0 op_sel_hi:[1,1,0]
	ds_read_b128 v[198:201], v57 offset:17264
	v_add_f32_e32 v250, v250, v251
	v_pk_fma_f32 v[246:247], v[206:207], v[86:87], v[246:247]
	v_pk_fma_f32 v[248:249], v[208:209], v[88:89], v[248:249]
	ds_read_b128 v[206:209], v57 offset:17280
	v_add_f32_e32 v202, v202, v203
	v_pk_fma_f32 v[246:247], v[210:211], v[90:91], v[246:247]
	v_pk_fma_f32 v[248:249], v[212:213], v[92:93], v[248:249]
	ds_read_b128 v[210:213], v57 offset:17296
	v_lshlrev_b32_e32 v227, 16, v227
	v_pk_fma_f32 v[246:247], v[190:191], v[94:95], v[246:247]
	v_pk_fma_f32 v[248:249], v[192:193], v[96:97], v[248:249]
	ds_read_b128 v[190:193], v57 offset:17312
	v_add_f32_e32 v250, v250, v202
	v_pk_fma_f32 v[246:247], v[194:195], v[98:99], v[246:247]
	v_pk_fma_f32 v[248:249], v[196:197], v[100:101], v[248:249]
	ds_read_b128 v[194:197], v57 offset:17328
	v_add_f32_e32 v250, v250, v111
	s_waitcnt lgkmcnt(5)
	v_pk_fma_f32 v[246:247], v[214:215], v[102:103], v[246:247]
	v_pk_fma_f32 v[248:249], v[216:217], v[104:105], v[248:249]
	ds_read_b128 v[214:217], v57 offset:17344
	v_fma_f32 v111, v226, v227, -v250
	v_pk_fma_f32 v[246:247], v[238:239], v[106:107], v[246:247]
	v_pk_fma_f32 v[248:249], v[240:241], v[108:109], v[248:249]
	ds_read_b128 v[238:241], v57 offset:17360
	v_pk_fma_f32 v[246:247], v[242:243], v[110:111], v[246:247]
	v_pk_fma_f32 v[248:249], v[244:245], v[112:113], v[248:249]
	ds_read_b128 v[242:245], v57 offset:17376
	v_mad_u32_u24 v61, v55, 63, v51
	ds_read_u16 v221, v61
	ds_read_b32 v220, v53 offset:252
	s_waitcnt lgkmcnt(5)
	v_pk_fma_f32 v[250:251], v[198:199], v[34:35], 0 op_sel_hi:[1,1,0]
	v_pk_fma_f32 v[202:203], v[200:201], v[36:37], 0 op_sel_hi:[1,1,0]
	v_add_f32_e32 v246, v246, v247
	v_pk_fma_f32 v[250:251], v[206:207], v[86:87], v[250:251]
	v_pk_fma_f32 v[202:203], v[208:209], v[88:89], v[202:203]
	v_add_f32_e32 v248, v248, v249
	v_pk_fma_f32 v[250:251], v[210:211], v[90:91], v[250:251]
	v_pk_fma_f32 v[202:203], v[212:213], v[92:93], v[202:203]
	v_lshlrev_b32_e32 v59, 16, v59
	v_pk_fma_f32 v[250:251], v[190:191], v[94:95], v[250:251]
	v_pk_fma_f32 v[202:203], v[192:193], v[96:97], v[202:203]
	v_add_f32_e32 v246, v246, v248
	v_pk_fma_f32 v[250:251], v[194:195], v[98:99], v[250:251]
	v_pk_fma_f32 v[202:203], v[196:197], v[100:101], v[202:203]
	v_add_f32_e32 v246, v246, v112
	s_waitcnt lgkmcnt(4)
	v_pk_fma_f32 v[250:251], v[214:215], v[102:103], v[250:251]
	v_pk_fma_f32 v[202:203], v[216:217], v[104:105], v[202:203]
	v_fma_f32 v112, v204, v59, -v246
	s_waitcnt lgkmcnt(3)
	v_pk_fma_f32 v[250:251], v[238:239], v[106:107], v[250:251]
	v_pk_fma_f32 v[202:203], v[240:241], v[108:109], v[202:203]
	s_waitcnt lgkmcnt(2)
	v_pk_fma_f32 v[250:251], v[242:243], v[110:111], v[250:251]
	v_pk_fma_f32 v[202:203], v[244:245], v[112:113], v[202:203]
	v_add_f32_e32 v250, v250, v251
	v_add_f32_e32 v202, v202, v203
	s_waitcnt lgkmcnt(0)
	v_lshlrev_b32_e32 v221, 16, v221
	v_add_f32_e32 v250, v250, v202
	v_add_f32_e32 v250, v250, v113
	v_fma_f32 v2, v220, v221, -v250
	s_and_saveexec_b64 s[0:1], vcc
	s_xor_b64 s[0:1], exec, s[0:1]
	s_cbranch_execz .LBB0_194
	v_lshl_add_u32 v47, v47, 1, 0
	v_bfe_u32 v49, v0, 16, 1
	v_add_u32_e32 v47, 0x1d900, v47
	v_add3_u32 v0, v0, v49, s33
	ds_write_b16_d16_hi v47, v0
	v_bfe_u32 v0, v3, 16, 1
	v_add3_u32 v0, v3, v0, s33
	ds_write_b16_d16_hi v47, v0 offset:256
	v_bfe_u32 v0, v4, 16, 1
	v_add3_u32 v0, v4, v0, s33
	ds_write_b16_d16_hi v47, v0 offset:512
	v_bfe_u32 v0, v5, 16, 1
	v_add3_u32 v0, v5, v0, s33
	ds_write_b16_d16_hi v47, v0 offset:768
	v_bfe_u32 v0, v6, 16, 1
	v_add3_u32 v0, v6, v0, s33
	ds_write_b16_d16_hi v47, v0 offset:1024
	v_bfe_u32 v0, v7, 16, 1
	v_add3_u32 v0, v7, v0, s33
	ds_write_b16_d16_hi v47, v0 offset:1280
	v_bfe_u32 v0, v8, 16, 1
	v_add3_u32 v0, v8, v0, s33
	ds_write_b16_d16_hi v47, v0 offset:1536
	v_bfe_u32 v0, v9, 16, 1
	v_add3_u32 v0, v9, v0, s33
	ds_write_b16_d16_hi v47, v0 offset:1792
	v_bfe_u32 v0, v10, 16, 1
	v_add3_u32 v0, v10, v0, s33
	ds_write_b16_d16_hi v47, v0 offset:2048
	v_bfe_u32 v0, v11, 16, 1
	v_add3_u32 v0, v11, v0, s33
	ds_write_b16_d16_hi v47, v0 offset:2304
	v_bfe_u32 v0, v12, 16, 1
	v_add3_u32 v0, v12, v0, s33
	ds_write_b16_d16_hi v47, v0 offset:2560
	v_bfe_u32 v0, v13, 16, 1
	v_add3_u32 v0, v13, v0, s33
	ds_write_b16_d16_hi v47, v0 offset:2816
	v_bfe_u32 v0, v14, 16, 1
	v_add3_u32 v0, v14, v0, s33
	ds_write_b16_d16_hi v47, v0 offset:3072
	v_bfe_u32 v0, v15, 16, 1
	v_add3_u32 v0, v15, v0, s33
	ds_write_b16_d16_hi v47, v0 offset:3328
	v_bfe_u32 v0, v16, 16, 1
	v_add3_u32 v0, v16, v0, s33
	ds_write_b16_d16_hi v47, v0 offset:3584
	v_bfe_u32 v0, v17, 16, 1
	v_add3_u32 v0, v17, v0, s33
	ds_write_b16_d16_hi v47, v0 offset:3840
	v_bfe_u32 v0, v18, 16, 1
	v_add3_u32 v0, v18, v0, s33
	ds_write_b16_d16_hi v47, v0 offset:4096
	v_bfe_u32 v0, v19, 16, 1
	v_add3_u32 v0, v19, v0, s33
	ds_write_b16_d16_hi v47, v0 offset:4352
	v_bfe_u32 v0, v20, 16, 1
	v_add3_u32 v0, v20, v0, s33
	ds_write_b16_d16_hi v47, v0 offset:4608
	v_bfe_u32 v0, v21, 16, 1
	v_add3_u32 v0, v21, v0, s33
	ds_write_b16_d16_hi v47, v0 offset:4864
	v_bfe_u32 v0, v22, 16, 1
	v_add3_u32 v0, v22, v0, s33
	ds_write_b16_d16_hi v47, v0 offset:5120
	v_bfe_u32 v0, v23, 16, 1
	v_add3_u32 v0, v23, v0, s33
	ds_write_b16_d16_hi v47, v0 offset:5376
	v_bfe_u32 v0, v24, 16, 1
	v_add3_u32 v0, v24, v0, s33
	ds_write_b16_d16_hi v47, v0 offset:5632
	v_bfe_u32 v0, v25, 16, 1
	v_add3_u32 v0, v25, v0, s33
	ds_write_b16_d16_hi v47, v0 offset:5888
	v_bfe_u32 v0, v26, 16, 1
	v_add3_u32 v0, v26, v0, s33
	ds_write_b16_d16_hi v47, v0 offset:6144
	v_bfe_u32 v0, v27, 16, 1
	v_add3_u32 v0, v27, v0, s33
	ds_write_b16_d16_hi v47, v0 offset:6400
	v_bfe_u32 v0, v28, 16, 1
	v_add3_u32 v0, v28, v0, s33
	ds_write_b16_d16_hi v47, v0 offset:6656
	v_bfe_u32 v0, v29, 16, 1
	v_add3_u32 v0, v29, v0, s33
	ds_write_b16_d16_hi v47, v0 offset:6912
	v_bfe_u32 v0, v30, 16, 1
	v_add3_u32 v0, v30, v0, s33
	ds_write_b16_d16_hi v47, v0 offset:7168
	v_bfe_u32 v0, v31, 16, 1
	v_add3_u32 v0, v31, v0, s33
	ds_write_b16_d16_hi v47, v0 offset:7424
	v_bfe_u32 v0, v32, 16, 1
	v_add3_u32 v0, v32, v0, s33
	ds_write_b16_d16_hi v47, v0 offset:7680
	v_bfe_u32 v0, v33, 16, 1
	v_add3_u32 v0, v33, v0, s33
	ds_write_b16_d16_hi v47, v0 offset:7936
	v_bfe_u32 v0, v34, 16, 1
	v_add3_u32 v0, v34, v0, s33
	ds_write_b16_d16_hi v47, v0 offset:8192
	v_bfe_u32 v0, v35, 16, 1
	v_add3_u32 v0, v35, v0, s33
	ds_write_b16_d16_hi v47, v0 offset:8448
	v_bfe_u32 v0, v36, 16, 1
	v_add3_u32 v0, v36, v0, s33
	ds_write_b16_d16_hi v47, v0 offset:8704
	v_bfe_u32 v0, v37, 16, 1
	v_add3_u32 v0, v37, v0, s33
	ds_write_b16_d16_hi v47, v0 offset:8960
	v_bfe_u32 v0, v86, 16, 1
	v_add3_u32 v0, v86, v0, s33
	ds_write_b16_d16_hi v47, v0 offset:9216
	v_bfe_u32 v0, v87, 16, 1
	v_add3_u32 v0, v87, v0, s33
	ds_write_b16_d16_hi v47, v0 offset:9472
	v_bfe_u32 v0, v88, 16, 1
	v_add3_u32 v0, v88, v0, s33
	ds_write_b16_d16_hi v47, v0 offset:9728
	v_bfe_u32 v0, v89, 16, 1
	v_add3_u32 v0, v89, v0, s33
	ds_write_b16_d16_hi v47, v0 offset:9984
	v_bfe_u32 v0, v90, 16, 1
	v_add3_u32 v0, v90, v0, s33
	ds_write_b16_d16_hi v47, v0 offset:10240
	v_bfe_u32 v0, v91, 16, 1
	v_add3_u32 v0, v91, v0, s33
	ds_write_b16_d16_hi v47, v0 offset:10496
	v_bfe_u32 v0, v92, 16, 1
	v_add3_u32 v0, v92, v0, s33
	ds_write_b16_d16_hi v47, v0 offset:10752
	v_bfe_u32 v0, v93, 16, 1
	v_add3_u32 v0, v93, v0, s33
	ds_write_b16_d16_hi v47, v0 offset:11008
	v_bfe_u32 v0, v94, 16, 1
	v_add3_u32 v0, v94, v0, s33
	ds_write_b16_d16_hi v47, v0 offset:11264
	v_bfe_u32 v0, v95, 16, 1
	v_add3_u32 v0, v95, v0, s33
	ds_write_b16_d16_hi v47, v0 offset:11520
	v_bfe_u32 v0, v96, 16, 1
	v_add3_u32 v0, v96, v0, s33
	ds_write_b16_d16_hi v47, v0 offset:11776
	v_bfe_u32 v0, v97, 16, 1
	v_add3_u32 v0, v97, v0, s33
	ds_write_b16_d16_hi v47, v0 offset:12032
	v_bfe_u32 v0, v98, 16, 1
	v_add3_u32 v0, v98, v0, s33
	ds_write_b16_d16_hi v47, v0 offset:12288
	v_bfe_u32 v0, v99, 16, 1
	v_add3_u32 v0, v99, v0, s33
	ds_write_b16_d16_hi v47, v0 offset:12544
	v_bfe_u32 v0, v100, 16, 1
	v_add3_u32 v0, v100, v0, s33
	ds_write_b16_d16_hi v47, v0 offset:12800
	v_bfe_u32 v0, v101, 16, 1
	v_add3_u32 v0, v101, v0, s33
	ds_write_b16_d16_hi v47, v0 offset:13056
	v_bfe_u32 v0, v102, 16, 1
	v_add3_u32 v0, v102, v0, s33
	ds_write_b16_d16_hi v47, v0 offset:13312
	v_bfe_u32 v0, v103, 16, 1
	v_add3_u32 v0, v103, v0, s33
	ds_write_b16_d16_hi v47, v0 offset:13568
	v_bfe_u32 v0, v104, 16, 1
	v_add3_u32 v0, v104, v0, s33
	ds_write_b16_d16_hi v47, v0 offset:13824
	v_bfe_u32 v0, v105, 16, 1
	v_add3_u32 v0, v105, v0, s33
	ds_write_b16_d16_hi v47, v0 offset:14080
	v_bfe_u32 v0, v106, 16, 1
	v_add3_u32 v0, v106, v0, s33
	ds_write_b16_d16_hi v47, v0 offset:14336
	v_bfe_u32 v0, v107, 16, 1
	v_add3_u32 v0, v107, v0, s33
	ds_write_b16_d16_hi v47, v0 offset:14592
	v_bfe_u32 v0, v108, 16, 1
	v_add3_u32 v0, v108, v0, s33
	ds_write_b16_d16_hi v47, v0 offset:14848
	v_bfe_u32 v0, v109, 16, 1
	v_add3_u32 v0, v109, v0, s33
	ds_write_b16_d16_hi v47, v0 offset:15104
	v_bfe_u32 v0, v110, 16, 1
	v_add3_u32 v0, v110, v0, s33
	ds_write_b16_d16_hi v47, v0 offset:15360
	v_bfe_u32 v0, v111, 16, 1
	v_add3_u32 v0, v111, v0, s33
	ds_write_b16_d16_hi v47, v0 offset:15616
	v_bfe_u32 v0, v112, 16, 1
	v_add3_u32 v0, v112, v0, s33
	ds_write_b16_d16_hi v47, v0 offset:15872
	v_bfe_u32 v0, v2, 16, 1
	v_add3_u32 v0, v2, v0, s33
	ds_write_b16_d16_hi v47, v0 offset:16128
